# v3 (static prio waves 4-7) plus: redundant hipcc s_waitcnt lgkmcnt(0) after each pre-MMA barrier deleted (LDS already drained by the inline wait before the barrier)
# baseline (speedup 1.0000x reference)
; #define WAIT_V(n) asm volatile("s_waitcnt vmcnt(" #n ")" ::: "memory")
; #define WAIT_L(n) asm volatile("s_waitcnt lgkmcnt(" #n ")" ::: "memory")
; #define BAR __builtin_amdgcn_s_barrier()
; #define SCHED __builtin_amdgcn_sched_barrier(0)
; #define STG_A(b, h, ptr) do { const char* _g = (ptr) + (h) * ahalf; LAS unsigned char* _l = lw + ((b) * 2 + (h)) * 16384; GLDS(_g + voa0, _l); GLDS(_g + voa1, _l + 8192); } while (0)
; #define STG_B(b, h, ptr) do { const char* _g = (ptr) + (h) * bhalf; LAS unsigned char* _l = lw + 65536 + ((b) * 2 + (h)) * 16384; GLDS(_g + vob0, _l); GLDS(_g + vob1, _l + 8192); } while (0)
; #define LDA(dst, b, h) _Pragma("unroll") for (int m = 0; m < 4; ++m) _Pragma("unroll") for (int k = 0; k < 2; ++k) dst[m][k] = *(const LAS bf16x8*)(la + ((b) * 2 + (h)) * 16384 + m * 2048 + k * 1024)
; #define LDB(dst, b, h) _Pragma("unroll") for (int n = 0; n < 2; ++n) _Pragma("unroll") for (int k = 0; k < 2; ++k) dst[n][k] = *(const LAS bf16x8*)(lb + ((b) * 2 + (h)) * 16384 + n * 2048 + k * 1024)
; #define MMA(ai, bj, Af, Bf) do { __builtin_amdgcn_s_setprio(1); \
;     _Pragma("unroll") for (int m = 0; m < 4; ++m) _Pragma("unroll") for (int n = 0; n < 2; ++n) _Pragma("unroll") for (int k = 0; k < 2; ++k) \
;         acc[ai][bj][m][n] = __builtin_amdgcn_mfma_f32_16x16x32_bf16(Bf[n][k], Af[m][k], acc[ai][bj][m][n], 0, 0, 0); \
;     __builtin_amdgcn_s_setprio(0); } while (0)
; template <int BMODE, class Epi, class TileFn>
; DEV void gemm_loop(LAS unsigned char* lds, const bf16_t* __restrict__ A, int lda, const bf16_t* __restrict__ B, int ldb, int K, const Epi& epi, int t0, int tstep, int tend, const TileFn& tf) {
;     ...
;         for (int t = 0; t < nt; t += 2) {
;             const bool last = (t == nt - 2);
;             const char* a1 = cA + (size_t)(t + 1) * 128;
;             const char* a2 = last ? nA : cA + (size_t)(t + 2) * 128;
;             const char* b2 = last ? nB : cB + (size_t)(t + 2) * bks;
;             const char* a3 = a2 + 128; const char* b3 = b2 + bks;
;             LDB(B0, 0, 0); LDB(B1, 0, 1); SCHED; LDA(At, 0, 0); STG_A(1, 1, a1);
;             WAIT_V(8); WAIT_L(0); BAR; MMA(0, 0, At, B0); MMA(0, 1, At, B1); BAR; SCHED;
;             LDA(At, 0, 1); STG_B(0, 0, b2); STG_B(0, 1, b2); STG_A(0, 0, a2);
;             WAIT_V(8); WAIT_L(0); BAR; MMA(1, 0, At, B0); MMA(1, 1, At, B1); BAR; SCHED;
.Lsp_441:
	ds_read_b128 v[162:165], v160
	ds_read_b128 v[166:169], v160 offset:1024
	ds_read_b128 v[170:173], v160 offset:2048
	ds_read_b128 v[174:177], v160 offset:3072
	ds_read_b128 v[178:181], v160 offset:16384
	ds_read_b128 v[182:185], v160 offset:17408
	ds_read_b128 v[196:199], v160 offset:18432
	ds_read_b128 v[200:203], v160 offset:19456
	s_add_u32 s8, s55, s36
	s_addc_u32 s9, s74, s37
	s_add_u32 s8, s8, 0x62e6100
	s_addc_u32 s9, s9, 0
	s_add_u32 s31, s75, s36
	s_addc_u32 s93, s83, s37
	s_cmpk_eq_i32 s36, 0x700
	s_cselect_b32 s45, s30, s9
	s_cselect_b32 s44, s29, s8
	s_cselect_b32 s9, s53, s93
	s_cselect_b32 s8, s50, s31
	v_add_u32_e32 v194, 0xc000, v145
	v_lshl_add_u64 v[186:187], v[140:141], 0, s[36:37]
	v_readfirstlane_b32 s31, v194
	v_add_u32_e32 v194, 0xe000, v145
	s_mov_b32 m0, s31
	v_readfirstlane_b32 s31, v194
	ds_read_b128 v[212:215], v161
	ds_read_b128 v[216:219], v161 offset:1024
	ds_read_b128 v[220:223], v161 offset:2048
	ds_read_b128 v[224:227], v161 offset:3072
	ds_read_b128 v[228:231], v161 offset:4096
	ds_read_b128 v[232:235], v161 offset:5120
	ds_read_b128 v[236:239], v161 offset:6144
	ds_read_b128 v[240:243], v161 offset:7168
	global_load_lds_dwordx4 v[186:187], off
	v_lshl_add_u64 v[186:187], v[142:143], 0, s[36:37]
	s_mov_b32 m0, s31
	s_nop 0
	global_load_lds_dwordx4 v[186:187], off
	s_waitcnt vmcnt(8)
	s_waitcnt lgkmcnt(0)
	s_barrier
	v_mfma_f32_16x16x32_bf16 v[124:127], v[162:165], v[212:215], 0
	v_mfma_f32_16x16x32_bf16 v[120:123], v[170:173], v[212:215], 0
	v_mfma_f32_16x16x32_bf16 v[108:111], v[162:165], v[220:223], 0
	v_mfma_f32_16x16x32_bf16 v[104:107], v[170:173], v[220:223], 0
	v_mfma_f32_16x16x32_bf16 v[92:95], v[162:165], v[228:231], 0
	v_mfma_f32_16x16x32_bf16 v[88:91], v[170:173], v[228:231], 0
	v_mfma_f32_16x16x32_bf16 v[76:79], v[162:165], v[236:239], 0
	v_mfma_f32_16x16x32_bf16 v[72:75], v[170:173], v[236:239], 0
	v_mfma_f32_16x16x32_bf16 v[124:127], v[166:169], v[216:219], v[124:127]
	v_mfma_f32_16x16x32_bf16 v[120:123], v[174:177], v[216:219], v[120:123]
	v_mfma_f32_16x16x32_bf16 v[108:111], v[166:169], v[224:227], v[108:111]
	v_mfma_f32_16x16x32_bf16 v[104:107], v[174:177], v[224:227], v[104:107]
	v_mfma_f32_16x16x32_bf16 v[92:95], v[166:169], v[232:235], v[92:95]
	v_mfma_f32_16x16x32_bf16 v[88:91], v[174:177], v[232:235], v[88:91]
	v_mfma_f32_16x16x32_bf16 v[76:79], v[166:169], v[240:243], v[76:79]
	v_mfma_f32_16x16x32_bf16 v[72:75], v[174:177], v[240:243], v[72:75]
	v_mfma_f32_16x16x32_bf16 v[116:119], v[178:181], v[212:215], 0
	v_mfma_f32_16x16x32_bf16 v[112:115], v[196:199], v[212:215], 0
	v_mfma_f32_16x16x32_bf16 v[100:103], v[178:181], v[220:223], 0
	v_mfma_f32_16x16x32_bf16 v[96:99], v[196:199], v[220:223], 0
	v_mfma_f32_16x16x32_bf16 v[84:87], v[178:181], v[228:231], 0
	v_mfma_f32_16x16x32_bf16 v[80:83], v[196:199], v[228:231], 0
	v_mfma_f32_16x16x32_bf16 v[68:71], v[178:181], v[236:239], 0
	v_mfma_f32_16x16x32_bf16 v[64:67], v[196:199], v[236:239], 0
	v_mfma_f32_16x16x32_bf16 v[116:119], v[182:185], v[216:219], v[116:119]
	v_mfma_f32_16x16x32_bf16 v[112:115], v[200:203], v[216:219], v[112:115]
	v_mfma_f32_16x16x32_bf16 v[100:103], v[182:185], v[224:227], v[100:103]
	v_mfma_f32_16x16x32_bf16 v[96:99], v[200:203], v[224:227], v[96:99]
	v_mfma_f32_16x16x32_bf16 v[84:87], v[182:185], v[232:235], v[84:87]
	v_mfma_f32_16x16x32_bf16 v[80:83], v[200:203], v[232:235], v[80:83]
	v_mfma_f32_16x16x32_bf16 v[68:71], v[182:185], v[240:243], v[68:71]
	v_mfma_f32_16x16x32_bf16 v[64:67], v[200:203], v[240:243], v[64:67]
	s_barrier
	v_readfirstlane_b32 s31, v146
	v_lshl_add_u64 v[186:187], s[8:9], 0, v[130:131]
	s_mov_b32 m0, s31
	v_readfirstlane_b32 s31, v147
	s_add_u32 s94, s8, 0x40000
	ds_read_b128 v[212:215], v161 offset:16384
	ds_read_b128 v[216:219], v161 offset:17408
	ds_read_b128 v[220:223], v161 offset:18432
	ds_read_b128 v[224:227], v161 offset:19456
	ds_read_b128 v[228:231], v161 offset:20480
	ds_read_b128 v[232:235], v161 offset:21504
	ds_read_b128 v[236:239], v161 offset:22528
	ds_read_b128 v[240:243], v161 offset:23552
	global_load_lds_dwordx4 v[186:187], off
	v_lshl_add_u64 v[204:205], s[8:9], 0, v[132:133]
	s_mov_b32 m0, s31
	s_addc_u32 s95, s9, 0
	v_readfirstlane_b32 s31, v148
	global_load_lds_dwordx4 v[204:205], off
	v_lshl_add_u64 v[244:245], s[94:95], 0, v[130:131]
	s_mov_b32 m0, s31
	v_readfirstlane_b32 s31, v149
	global_load_lds_dwordx4 v[244:245], off
	v_lshl_add_u64 v[244:245], s[94:95], 0, v[132:133]
	s_mov_b32 m0, s31
	v_readfirstlane_b32 s31, v145
	global_load_lds_dwordx4 v[244:245], off
	v_lshl_add_u64 v[244:245], s[44:45], 0, v[128:129]
	s_mov_b32 m0, s31
	v_readfirstlane_b32 s31, v150
	global_load_lds_dwordx4 v[244:245], off
	v_lshl_add_u64 v[246:247], s[44:45], 0, v[134:135]
	s_mov_b32 m0, s31
	s_nop 0
	global_load_lds_dwordx4 v[246:247], off
	s_waitcnt vmcnt(8)
	s_waitcnt lgkmcnt(0)
	s_barrier
	v_mfma_f32_16x16x32_bf16 v[60:63], v[162:165], v[212:215], 0
	v_mfma_f32_16x16x32_bf16 v[56:59], v[170:173], v[212:215], 0
	v_mfma_f32_16x16x32_bf16 v[44:47], v[162:165], v[220:223], 0
	v_mfma_f32_16x16x32_bf16 v[40:43], v[170:173], v[220:223], 0
	v_mfma_f32_16x16x32_bf16 v[28:31], v[162:165], v[228:231], 0
	v_mfma_f32_16x16x32_bf16 v[24:27], v[170:173], v[228:231], 0
	v_mfma_f32_16x16x32_bf16 v[12:15], v[162:165], v[236:239], 0
	v_mfma_f32_16x16x32_bf16 v[8:11], v[170:173], v[236:239], 0
	v_mfma_f32_16x16x32_bf16 v[60:63], v[166:169], v[216:219], v[60:63]
	v_mfma_f32_16x16x32_bf16 v[56:59], v[174:177], v[216:219], v[56:59]
	v_mfma_f32_16x16x32_bf16 v[44:47], v[166:169], v[224:227], v[44:47]
	v_mfma_f32_16x16x32_bf16 v[40:43], v[174:177], v[224:227], v[40:43]
	v_mfma_f32_16x16x32_bf16 v[28:31], v[166:169], v[232:235], v[28:31]
	v_mfma_f32_16x16x32_bf16 v[24:27], v[174:177], v[232:235], v[24:27]
	v_mfma_f32_16x16x32_bf16 v[12:15], v[166:169], v[240:243], v[12:15]
	v_mfma_f32_16x16x32_bf16 v[8:11], v[174:177], v[240:243], v[8:11]
	v_mfma_f32_16x16x32_bf16 v[52:55], v[178:181], v[212:215], 0
	v_mfma_f32_16x16x32_bf16 v[48:51], v[196:199], v[212:215], 0
	v_mfma_f32_16x16x32_bf16 v[36:39], v[178:181], v[220:223], 0
	v_mfma_f32_16x16x32_bf16 v[32:35], v[196:199], v[220:223], 0
	v_mfma_f32_16x16x32_bf16 v[20:23], v[178:181], v[228:231], 0
	v_mfma_f32_16x16x32_bf16 v[16:19], v[196:199], v[228:231], 0
	v_mfma_f32_16x16x32_bf16 v[4:7], v[178:181], v[236:239], 0
	v_mfma_f32_16x16x32_bf16 v[0:3], v[196:199], v[236:239], 0
	v_mfma_f32_16x16x32_bf16 v[52:55], v[182:185], v[216:219], v[52:55]
	v_mfma_f32_16x16x32_bf16 v[48:51], v[200:203], v[216:219], v[48:51]
	v_mfma_f32_16x16x32_bf16 v[36:39], v[182:185], v[224:227], v[36:39]
	v_mfma_f32_16x16x32_bf16 v[32:35], v[200:203], v[224:227], v[32:35]
	v_mfma_f32_16x16x32_bf16 v[20:23], v[182:185], v[232:235], v[20:23]
	v_mfma_f32_16x16x32_bf16 v[16:19], v[200:203], v[232:235], v[16:19]
	v_mfma_f32_16x16x32_bf16 v[4:7], v[182:185], v[240:243], v[4:7]
	v_mfma_f32_16x16x32_bf16 v[0:3], v[200:203], v[240:243], v[0:3]
	s_barrier
	s_branch .Lkmid_441
; #define WAIT_V(n) asm volatile("s_waitcnt vmcnt(" #n ")" ::: "memory")
; #define WAIT_L(n) asm volatile("s_waitcnt lgkmcnt(" #n ")" ::: "memory")
; #define BAR __builtin_amdgcn_s_barrier()
; #define SCHED __builtin_amdgcn_sched_barrier(0)
; #define STG_A(b, h, ptr) do { const char* _g = (ptr) + (h) * ahalf; LAS unsigned char* _l = lw + ((b) * 2 + (h)) * 16384; GLDS(_g + voa0, _l); GLDS(_g + voa1, _l + 8192); } while (0)
; #define STG_B(b, h, ptr) do { const char* _g = (ptr) + (h) * bhalf; LAS unsigned char* _l = lw + 65536 + ((b) * 2 + (h)) * 16384; GLDS(_g + vob0, _l); GLDS(_g + vob1, _l + 8192); } while (0)
; #define LDA(dst, b, h) _Pragma("unroll") for (int m = 0; m < 4; ++m) _Pragma("unroll") for (int k = 0; k < 2; ++k) dst[m][k] = *(const LAS bf16x8*)(la + ((b) * 2 + (h)) * 16384 + m * 2048 + k * 1024)
; #define LDB(dst, b, h) _Pragma("unroll") for (int n = 0; n < 2; ++n) _Pragma("unroll") for (int k = 0; k < 2; ++k) dst[n][k] = *(const LAS bf16x8*)(lb + ((b) * 2 + (h)) * 16384 + n * 2048 + k * 1024)
; #define MMA(ai, bj, Af, Bf) do { __builtin_amdgcn_s_setprio(1); \
;     _Pragma("unroll") for (int m = 0; m < 4; ++m) _Pragma("unroll") for (int n = 0; n < 2; ++n) _Pragma("unroll") for (int k = 0; k < 2; ++k) \
;         acc[ai][bj][m][n] = __builtin_amdgcn_mfma_f32_16x16x32_bf16(Bf[n][k], Af[m][k], acc[ai][bj][m][n], 0, 0, 0); \
;     __builtin_amdgcn_s_setprio(0); } while (0)
; template <int BMODE, class Epi, class TileFn>
; DEV void gemm_loop(LAS unsigned char* lds, const bf16_t* __restrict__ A, int lda, const bf16_t* __restrict__ B, int ldb, int K, const Epi& epi, int t0, int tstep, int tend, const TileFn& tf) {
;     ...
;         for (int t = 0; t < nt; t += 2) {
;             const bool last = (t == nt - 2);
;             const char* a1 = cA + (size_t)(t + 1) * 128;
;             const char* a2 = last ? nA : cA + (size_t)(t + 2) * 128;
;             const char* b2 = last ? nB : cB + (size_t)(t + 2) * bks;
;             const char* a3 = a2 + 128; const char* b3 = b2 + bks;
;             LDB(B0, 0, 0); LDB(B1, 0, 1); SCHED; LDA(At, 0, 0); STG_A(1, 1, a1);
;             WAIT_V(8); WAIT_L(0); BAR; MMA(0, 0, At, B0); MMA(0, 1, At, B1); BAR; SCHED;
;             LDA(At, 0, 1); STG_B(0, 0, b2); STG_B(0, 1, b2); STG_A(0, 0, a2);
;             WAIT_V(8); WAIT_L(0); BAR; MMA(1, 0, At, B0); MMA(1, 1, At, B1); BAR; SCHED;
.LBB0_441:
	ds_read_b128 v[162:165], v160
	ds_read_b128 v[166:169], v160 offset:1024
	ds_read_b128 v[170:173], v160 offset:2048
	ds_read_b128 v[174:177], v160 offset:3072
	ds_read_b128 v[178:181], v160 offset:16384
	ds_read_b128 v[182:185], v160 offset:17408
	ds_read_b128 v[196:199], v160 offset:18432
	ds_read_b128 v[200:203], v160 offset:19456
	s_add_u32 s8, s55, s36
	s_addc_u32 s9, s74, s37
	s_add_u32 s8, s8, 0x62e6100
	s_addc_u32 s9, s9, 0
	s_add_u32 s31, s75, s36
	s_addc_u32 s93, s83, s37
	s_cmpk_eq_i32 s36, 0x700
	s_cselect_b32 s45, s30, s9
	s_cselect_b32 s44, s29, s8
	s_cselect_b32 s9, s53, s93
	s_cselect_b32 s8, s50, s31
	v_add_u32_e32 v194, 0xc000, v145
	v_lshl_add_u64 v[186:187], v[140:141], 0, s[36:37]
	v_readfirstlane_b32 s31, v194
	v_add_u32_e32 v194, 0xe000, v145
	s_mov_b32 m0, s31
	v_readfirstlane_b32 s31, v194
	ds_read_b128 v[212:215], v161
	ds_read_b128 v[216:219], v161 offset:1024
	ds_read_b128 v[220:223], v161 offset:2048
	ds_read_b128 v[224:227], v161 offset:3072
	ds_read_b128 v[228:231], v161 offset:4096
	ds_read_b128 v[232:235], v161 offset:5120
	ds_read_b128 v[236:239], v161 offset:6144
	ds_read_b128 v[240:243], v161 offset:7168
	global_load_lds_dwordx4 v[186:187], off
	v_lshl_add_u64 v[186:187], v[142:143], 0, s[36:37]
	s_mov_b32 m0, s31
	s_nop 0
	global_load_lds_dwordx4 v[186:187], off
	s_waitcnt vmcnt(8)
	s_waitcnt lgkmcnt(0)
	s_barrier
	v_mfma_f32_16x16x32_bf16 v[124:127], v[162:165], v[212:215], v[124:127]
	v_mfma_f32_16x16x32_bf16 v[120:123], v[170:173], v[212:215], v[120:123]
	v_mfma_f32_16x16x32_bf16 v[108:111], v[162:165], v[220:223], v[108:111]
	v_mfma_f32_16x16x32_bf16 v[104:107], v[170:173], v[220:223], v[104:107]
	v_mfma_f32_16x16x32_bf16 v[92:95], v[162:165], v[228:231], v[92:95]
	v_mfma_f32_16x16x32_bf16 v[88:91], v[170:173], v[228:231], v[88:91]
	v_mfma_f32_16x16x32_bf16 v[76:79], v[162:165], v[236:239], v[76:79]
	v_mfma_f32_16x16x32_bf16 v[72:75], v[170:173], v[236:239], v[72:75]
	v_mfma_f32_16x16x32_bf16 v[124:127], v[166:169], v[216:219], v[124:127]
	v_mfma_f32_16x16x32_bf16 v[120:123], v[174:177], v[216:219], v[120:123]
	v_mfma_f32_16x16x32_bf16 v[108:111], v[166:169], v[224:227], v[108:111]
	v_mfma_f32_16x16x32_bf16 v[104:107], v[174:177], v[224:227], v[104:107]
	v_mfma_f32_16x16x32_bf16 v[92:95], v[166:169], v[232:235], v[92:95]
	v_mfma_f32_16x16x32_bf16 v[88:91], v[174:177], v[232:235], v[88:91]
	v_mfma_f32_16x16x32_bf16 v[76:79], v[166:169], v[240:243], v[76:79]
	v_mfma_f32_16x16x32_bf16 v[72:75], v[174:177], v[240:243], v[72:75]
	v_mfma_f32_16x16x32_bf16 v[116:119], v[178:181], v[212:215], v[116:119]
	v_mfma_f32_16x16x32_bf16 v[112:115], v[196:199], v[212:215], v[112:115]
	v_mfma_f32_16x16x32_bf16 v[100:103], v[178:181], v[220:223], v[100:103]
	v_mfma_f32_16x16x32_bf16 v[96:99], v[196:199], v[220:223], v[96:99]
	v_mfma_f32_16x16x32_bf16 v[84:87], v[178:181], v[228:231], v[84:87]
	v_mfma_f32_16x16x32_bf16 v[80:83], v[196:199], v[228:231], v[80:83]
	v_mfma_f32_16x16x32_bf16 v[68:71], v[178:181], v[236:239], v[68:71]
	v_mfma_f32_16x16x32_bf16 v[64:67], v[196:199], v[236:239], v[64:67]
	v_mfma_f32_16x16x32_bf16 v[116:119], v[182:185], v[216:219], v[116:119]
	v_mfma_f32_16x16x32_bf16 v[112:115], v[200:203], v[216:219], v[112:115]
	v_mfma_f32_16x16x32_bf16 v[100:103], v[182:185], v[224:227], v[100:103]
	v_mfma_f32_16x16x32_bf16 v[96:99], v[200:203], v[224:227], v[96:99]
	v_mfma_f32_16x16x32_bf16 v[84:87], v[182:185], v[232:235], v[84:87]
	v_mfma_f32_16x16x32_bf16 v[80:83], v[200:203], v[232:235], v[80:83]
	v_mfma_f32_16x16x32_bf16 v[68:71], v[182:185], v[240:243], v[68:71]
	v_mfma_f32_16x16x32_bf16 v[64:67], v[200:203], v[240:243], v[64:67]
	s_barrier
	v_readfirstlane_b32 s31, v146
	v_lshl_add_u64 v[186:187], s[8:9], 0, v[130:131]
	s_mov_b32 m0, s31
	v_readfirstlane_b32 s31, v147
	s_add_u32 s94, s8, 0x40000
	ds_read_b128 v[212:215], v161 offset:16384
	ds_read_b128 v[216:219], v161 offset:17408
	ds_read_b128 v[220:223], v161 offset:18432
	ds_read_b128 v[224:227], v161 offset:19456
	ds_read_b128 v[228:231], v161 offset:20480
	ds_read_b128 v[232:235], v161 offset:21504
	ds_read_b128 v[236:239], v161 offset:22528
	ds_read_b128 v[240:243], v161 offset:23552
	global_load_lds_dwordx4 v[186:187], off
	v_lshl_add_u64 v[204:205], s[8:9], 0, v[132:133]
	s_mov_b32 m0, s31
	s_addc_u32 s95, s9, 0
	v_readfirstlane_b32 s31, v148
	global_load_lds_dwordx4 v[204:205], off
	v_lshl_add_u64 v[244:245], s[94:95], 0, v[130:131]
	s_mov_b32 m0, s31
	v_readfirstlane_b32 s31, v149
	global_load_lds_dwordx4 v[244:245], off
	v_lshl_add_u64 v[244:245], s[94:95], 0, v[132:133]
	s_mov_b32 m0, s31
	v_readfirstlane_b32 s31, v145
	global_load_lds_dwordx4 v[244:245], off
	v_lshl_add_u64 v[244:245], s[44:45], 0, v[128:129]
	s_mov_b32 m0, s31
	v_readfirstlane_b32 s31, v150
	global_load_lds_dwordx4 v[244:245], off
	v_lshl_add_u64 v[246:247], s[44:45], 0, v[134:135]
	s_mov_b32 m0, s31
	s_nop 0
	global_load_lds_dwordx4 v[246:247], off
	s_waitcnt vmcnt(8)
	s_waitcnt lgkmcnt(0)
	s_barrier
; #define WAIT_V(n) asm volatile("s_waitcnt vmcnt(" #n ")" ::: "memory")
; #define WAIT_L(n) asm volatile("s_waitcnt lgkmcnt(" #n ")" ::: "memory")
; #define BAR __builtin_amdgcn_s_barrier()
; #define SCHED __builtin_amdgcn_sched_barrier(0)
; #define STG_A(b, h, ptr) do { const char* _g = (ptr) + (h) * ahalf; LAS unsigned char* _l = lw + ((b) * 2 + (h)) * 16384; GLDS(_g + voa0, _l); GLDS(_g + voa1, _l + 8192); } while (0)
; #define LDA(dst, b, h) _Pragma("unroll") for (int m = 0; m < 4; ++m) _Pragma("unroll") for (int k = 0; k < 2; ++k) dst[m][k] = *(const LAS bf16x8*)(la + ((b) * 2 + (h)) * 16384 + m * 2048 + k * 1024)
; #define LDB(dst, b, h) _Pragma("unroll") for (int n = 0; n < 2; ++n) _Pragma("unroll") for (int k = 0; k < 2; ++k) dst[n][k] = *(const LAS bf16x8*)(lb + ((b) * 2 + (h)) * 16384 + n * 2048 + k * 1024)
; #define MMA(ai, bj, Af, Bf) do { __builtin_amdgcn_s_setprio(1); \
;     _Pragma("unroll") for (int m = 0; m < 4; ++m) _Pragma("unroll") for (int n = 0; n < 2; ++n) _Pragma("unroll") for (int k = 0; k < 2; ++k) \
;         acc[ai][bj][m][n] = __builtin_amdgcn_mfma_f32_16x16x32_bf16(Bf[n][k], Af[m][k], acc[ai][bj][m][n], 0, 0, 0); \
;     __builtin_amdgcn_s_setprio(0); } while (0)
; template <int BMODE, class Epi, class TileFn>
; DEV void gemm_loop(LAS unsigned char* lds, const bf16_t* __restrict__ A, int lda, const bf16_t* __restrict__ B, int ldb, int K, const Epi& epi, int t0, int tstep, int tend, const TileFn& tf) {
;     ...
;             WAIT_V(8); WAIT_L(0); BAR; MMA(1, 0, At, B0); MMA(1, 1, At, B1); BAR; SCHED;
;             LDB(B0, 1, 0); LDB(B1, 1, 1); SCHED; LDA(At, 1, 0); STG_A(0, 1, a2);
;             WAIT_V(8); WAIT_L(0); BAR; MMA(0, 0, At, B0); MMA(0, 1, At, B1); BAR; SCHED;
	v_mfma_f32_16x16x32_bf16 v[60:63], v[162:165], v[212:215], v[60:63]
	v_mfma_f32_16x16x32_bf16 v[56:59], v[170:173], v[212:215], v[56:59]
	v_mfma_f32_16x16x32_bf16 v[44:47], v[162:165], v[220:223], v[44:47]
	v_mfma_f32_16x16x32_bf16 v[40:43], v[170:173], v[220:223], v[40:43]
	v_mfma_f32_16x16x32_bf16 v[28:31], v[162:165], v[228:231], v[28:31]
	v_mfma_f32_16x16x32_bf16 v[24:27], v[170:173], v[228:231], v[24:27]
	v_mfma_f32_16x16x32_bf16 v[12:15], v[162:165], v[236:239], v[12:15]
	v_mfma_f32_16x16x32_bf16 v[8:11], v[170:173], v[236:239], v[8:11]
	v_mfma_f32_16x16x32_bf16 v[60:63], v[166:169], v[216:219], v[60:63]
	v_mfma_f32_16x16x32_bf16 v[56:59], v[174:177], v[216:219], v[56:59]
	v_mfma_f32_16x16x32_bf16 v[44:47], v[166:169], v[224:227], v[44:47]
	v_mfma_f32_16x16x32_bf16 v[40:43], v[174:177], v[224:227], v[40:43]
	v_mfma_f32_16x16x32_bf16 v[28:31], v[166:169], v[232:235], v[28:31]
	v_mfma_f32_16x16x32_bf16 v[24:27], v[174:177], v[232:235], v[24:27]
	v_mfma_f32_16x16x32_bf16 v[12:15], v[166:169], v[240:243], v[12:15]
	v_mfma_f32_16x16x32_bf16 v[8:11], v[174:177], v[240:243], v[8:11]
	v_mfma_f32_16x16x32_bf16 v[52:55], v[178:181], v[212:215], v[52:55]
	v_mfma_f32_16x16x32_bf16 v[48:51], v[196:199], v[212:215], v[48:51]
	v_mfma_f32_16x16x32_bf16 v[36:39], v[178:181], v[220:223], v[36:39]
	v_mfma_f32_16x16x32_bf16 v[32:35], v[196:199], v[220:223], v[32:35]
	v_mfma_f32_16x16x32_bf16 v[20:23], v[178:181], v[228:231], v[20:23]
	v_mfma_f32_16x16x32_bf16 v[16:19], v[196:199], v[228:231], v[16:19]
	v_mfma_f32_16x16x32_bf16 v[4:7], v[178:181], v[236:239], v[4:7]
	v_mfma_f32_16x16x32_bf16 v[0:3], v[196:199], v[236:239], v[0:3]
	v_mfma_f32_16x16x32_bf16 v[52:55], v[182:185], v[216:219], v[52:55]
	v_mfma_f32_16x16x32_bf16 v[48:51], v[200:203], v[216:219], v[48:51]
	v_mfma_f32_16x16x32_bf16 v[36:39], v[182:185], v[224:227], v[36:39]
	v_mfma_f32_16x16x32_bf16 v[32:35], v[200:203], v[224:227], v[32:35]
	v_mfma_f32_16x16x32_bf16 v[20:23], v[182:185], v[232:235], v[20:23]
	v_mfma_f32_16x16x32_bf16 v[16:19], v[200:203], v[232:235], v[16:19]
	v_mfma_f32_16x16x32_bf16 v[4:7], v[182:185], v[240:243], v[4:7]
	v_mfma_f32_16x16x32_bf16 v[0:3], v[200:203], v[240:243], v[0:3]
	s_barrier
.Lkmid_441:
	ds_read_b128 v[162:165], v160 offset:32768
	ds_read_b128 v[166:169], v160 offset:33792
	ds_read_b128 v[170:173], v160 offset:34816
	ds_read_b128 v[174:177], v160 offset:35840
	ds_read_b128 v[178:181], v160 offset:49152
	ds_read_b128 v[182:185], v160 offset:50176
	ds_read_b128 v[196:199], v160 offset:51200
	ds_read_b128 v[200:203], v160 offset:52224
	s_add_u32 s44, s44, 0x40000
	s_addc_u32 s45, s45, 0
	v_readfirstlane_b32 s31, v151
	v_lshl_add_u64 v[248:249], s[44:45], 0, v[128:129]
	s_mov_b32 m0, s31
	v_readfirstlane_b32 s31, v152
	ds_read_b128 v[212:215], v161 offset:32768
	ds_read_b128 v[216:219], v161 offset:33792
	ds_read_b128 v[220:223], v161 offset:34816
	ds_read_b128 v[224:227], v161 offset:35840
	ds_read_b128 v[228:231], v161 offset:36864
	ds_read_b128 v[232:235], v161 offset:37888
	ds_read_b128 v[236:239], v161 offset:38912
	ds_read_b128 v[240:243], v161 offset:39936
	global_load_lds_dwordx4 v[248:249], off
	v_lshl_add_u64 v[248:249], s[44:45], 0, v[134:135]
	s_mov_b32 m0, s31
	s_nop 0
	global_load_lds_dwordx4 v[248:249], off
	s_waitcnt vmcnt(8)
	s_waitcnt lgkmcnt(0)
	s_barrier
	v_mfma_f32_16x16x32_bf16 v[124:127], v[162:165], v[212:215], v[124:127]
	v_mfma_f32_16x16x32_bf16 v[120:123], v[170:173], v[212:215], v[120:123]
	v_mfma_f32_16x16x32_bf16 v[108:111], v[162:165], v[220:223], v[108:111]
	v_mfma_f32_16x16x32_bf16 v[104:107], v[170:173], v[220:223], v[104:107]
	v_mfma_f32_16x16x32_bf16 v[92:95], v[162:165], v[228:231], v[92:95]
	v_mfma_f32_16x16x32_bf16 v[88:91], v[170:173], v[228:231], v[88:91]
	v_mfma_f32_16x16x32_bf16 v[76:79], v[162:165], v[236:239], v[76:79]
	v_mfma_f32_16x16x32_bf16 v[72:75], v[170:173], v[236:239], v[72:75]
	v_mfma_f32_16x16x32_bf16 v[124:127], v[166:169], v[216:219], v[124:127]
	v_mfma_f32_16x16x32_bf16 v[120:123], v[174:177], v[216:219], v[120:123]
	v_mfma_f32_16x16x32_bf16 v[108:111], v[166:169], v[224:227], v[108:111]
	v_mfma_f32_16x16x32_bf16 v[104:107], v[174:177], v[224:227], v[104:107]
	v_mfma_f32_16x16x32_bf16 v[92:95], v[166:169], v[232:235], v[92:95]
	v_mfma_f32_16x16x32_bf16 v[88:91], v[174:177], v[232:235], v[88:91]
	v_mfma_f32_16x16x32_bf16 v[76:79], v[166:169], v[240:243], v[76:79]
	v_mfma_f32_16x16x32_bf16 v[72:75], v[174:177], v[240:243], v[72:75]
	v_mfma_f32_16x16x32_bf16 v[116:119], v[178:181], v[212:215], v[116:119]
	v_mfma_f32_16x16x32_bf16 v[112:115], v[196:199], v[212:215], v[112:115]
	v_mfma_f32_16x16x32_bf16 v[100:103], v[178:181], v[220:223], v[100:103]
	v_mfma_f32_16x16x32_bf16 v[96:99], v[196:199], v[220:223], v[96:99]
	v_mfma_f32_16x16x32_bf16 v[84:87], v[178:181], v[228:231], v[84:87]
	v_mfma_f32_16x16x32_bf16 v[80:83], v[196:199], v[228:231], v[80:83]
	v_mfma_f32_16x16x32_bf16 v[68:71], v[178:181], v[236:239], v[68:71]
	v_mfma_f32_16x16x32_bf16 v[64:67], v[196:199], v[236:239], v[64:67]
	v_mfma_f32_16x16x32_bf16 v[116:119], v[182:185], v[216:219], v[116:119]
	v_mfma_f32_16x16x32_bf16 v[112:115], v[200:203], v[216:219], v[112:115]
	v_mfma_f32_16x16x32_bf16 v[100:103], v[182:185], v[224:227], v[100:103]
	v_mfma_f32_16x16x32_bf16 v[96:99], v[200:203], v[224:227], v[96:99]
	v_mfma_f32_16x16x32_bf16 v[84:87], v[182:185], v[232:235], v[84:87]
	v_mfma_f32_16x16x32_bf16 v[80:83], v[200:203], v[232:235], v[80:83]
	v_mfma_f32_16x16x32_bf16 v[68:71], v[182:185], v[240:243], v[68:71]
	v_mfma_f32_16x16x32_bf16 v[64:67], v[200:203], v[240:243], v[64:67]
	s_barrier
; #define WAIT_V(n) asm volatile("s_waitcnt vmcnt(" #n ")" ::: "memory")
; #define WAIT_L(n) asm volatile("s_waitcnt lgkmcnt(" #n ")" ::: "memory")
; #define BAR __builtin_amdgcn_s_barrier()
; #define SCHED __builtin_amdgcn_sched_barrier(0)
; #define STG_A(b, h, ptr) do { const char* _g = (ptr) + (h) * ahalf; LAS unsigned char* _l = lw + ((b) * 2 + (h)) * 16384; GLDS(_g + voa0, _l); GLDS(_g + voa1, _l + 8192); } while (0)
; #define STG_B(b, h, ptr) do { const char* _g = (ptr) + (h) * bhalf; LAS unsigned char* _l = lw + 65536 + ((b) * 2 + (h)) * 16384; GLDS(_g + vob0, _l); GLDS(_g + vob1, _l + 8192); } while (0)
; #define LDA(dst, b, h) _Pragma("unroll") for (int m = 0; m < 4; ++m) _Pragma("unroll") for (int k = 0; k < 2; ++k) dst[m][k] = *(const LAS bf16x8*)(la + ((b) * 2 + (h)) * 16384 + m * 2048 + k * 1024)
; #define MMA(ai, bj, Af, Bf) do { __builtin_amdgcn_s_setprio(1); \
;     _Pragma("unroll") for (int m = 0; m < 4; ++m) _Pragma("unroll") for (int n = 0; n < 2; ++n) _Pragma("unroll") for (int k = 0; k < 2; ++k) \
;         acc[ai][bj][m][n] = __builtin_amdgcn_mfma_f32_16x16x32_bf16(Bf[n][k], Af[m][k], acc[ai][bj][m][n], 0, 0, 0); \
;     __builtin_amdgcn_s_setprio(0); } while (0)
; template <int BMODE, class Epi, class TileFn>
; DEV void gemm_loop(LAS unsigned char* lds, const bf16_t* __restrict__ A, int lda, const bf16_t* __restrict__ B, int ldb, int K, const Epi& epi, int t0, int tstep, int tend, const TileFn& tf) {
;     ...
;             LDA(At, 1, 1); STG_B(1, 0, b3); STG_B(1, 1, b3); STG_A(1, 0, a3);
;             WAIT_V(8); WAIT_L(0); BAR; MMA(1, 0, At, B0); MMA(1, 1, At, B1); BAR; SCHED;
;         }
;         if (wr == 0) BAR;
	v_readfirstlane_b32 s31, v153
	v_lshl_add_u64 v[186:187], v[186:187], 0, s[2:3]
	s_mov_b32 m0, s31
	v_readfirstlane_b32 s31, v154
	s_add_u32 s8, s8, 0x40080
	ds_read_b128 v[212:215], v161 offset:49152
	ds_read_b128 v[216:219], v161 offset:50176
	ds_read_b128 v[220:223], v161 offset:51200
	ds_read_b128 v[224:227], v161 offset:52224
	ds_read_b128 v[228:231], v161 offset:53248
	ds_read_b128 v[232:235], v161 offset:54272
	ds_read_b128 v[236:239], v161 offset:55296
	ds_read_b128 v[240:243], v161 offset:56320
	global_load_lds_dwordx4 v[186:187], off
	v_lshl_add_u64 v[186:187], v[204:205], 0, s[2:3]
	s_mov_b32 m0, s31
	s_addc_u32 s9, s9, 0
	v_readfirstlane_b32 s31, v157
	global_load_lds_dwordx4 v[186:187], off
	v_lshl_add_u64 v[186:187], s[8:9], 0, v[130:131]
	s_mov_b32 m0, s31
	s_nop 0
	global_load_lds_dwordx4 v[186:187], off
	v_lshl_add_u64 v[186:187], s[8:9], 0, v[132:133]
	v_readfirstlane_b32 s8, v158
	s_mov_b32 m0, s8
	v_readfirstlane_b32 s8, v155
	global_load_lds_dwordx4 v[186:187], off
	v_lshl_add_u64 v[186:187], v[244:245], 0, s[2:3]
	s_mov_b32 m0, s8
	v_readfirstlane_b32 s8, v156
	global_load_lds_dwordx4 v[186:187], off
	v_lshl_add_u64 v[186:187], v[246:247], 0, s[2:3]
	s_mov_b32 m0, s8
	s_nop 0
	global_load_lds_dwordx4 v[186:187], off
	s_waitcnt vmcnt(8)
	s_waitcnt lgkmcnt(0)
	s_barrier
	v_mfma_f32_16x16x32_bf16 v[60:63], v[162:165], v[212:215], v[60:63]
	v_mfma_f32_16x16x32_bf16 v[56:59], v[170:173], v[212:215], v[56:59]
	v_mfma_f32_16x16x32_bf16 v[44:47], v[162:165], v[220:223], v[44:47]
	v_mfma_f32_16x16x32_bf16 v[40:43], v[170:173], v[220:223], v[40:43]
	v_mfma_f32_16x16x32_bf16 v[28:31], v[162:165], v[228:231], v[28:31]
	v_mfma_f32_16x16x32_bf16 v[24:27], v[170:173], v[228:231], v[24:27]
	v_mfma_f32_16x16x32_bf16 v[12:15], v[162:165], v[236:239], v[12:15]
	v_mfma_f32_16x16x32_bf16 v[8:11], v[170:173], v[236:239], v[8:11]
	v_mfma_f32_16x16x32_bf16 v[60:63], v[166:169], v[216:219], v[60:63]
	v_mfma_f32_16x16x32_bf16 v[56:59], v[174:177], v[216:219], v[56:59]
	v_mfma_f32_16x16x32_bf16 v[44:47], v[166:169], v[224:227], v[44:47]
	v_mfma_f32_16x16x32_bf16 v[40:43], v[174:177], v[224:227], v[40:43]
	v_mfma_f32_16x16x32_bf16 v[28:31], v[166:169], v[232:235], v[28:31]
	v_mfma_f32_16x16x32_bf16 v[24:27], v[174:177], v[232:235], v[24:27]
	v_mfma_f32_16x16x32_bf16 v[12:15], v[166:169], v[240:243], v[12:15]
	v_mfma_f32_16x16x32_bf16 v[8:11], v[174:177], v[240:243], v[8:11]
	v_mfma_f32_16x16x32_bf16 v[52:55], v[178:181], v[212:215], v[52:55]
	v_mfma_f32_16x16x32_bf16 v[48:51], v[196:199], v[212:215], v[48:51]
	v_mfma_f32_16x16x32_bf16 v[36:39], v[178:181], v[220:223], v[36:39]
	v_mfma_f32_16x16x32_bf16 v[32:35], v[196:199], v[220:223], v[32:35]
	v_mfma_f32_16x16x32_bf16 v[20:23], v[178:181], v[228:231], v[20:23]
	v_mfma_f32_16x16x32_bf16 v[16:19], v[196:199], v[228:231], v[16:19]
	v_mfma_f32_16x16x32_bf16 v[4:7], v[178:181], v[236:239], v[4:7]
	v_mfma_f32_16x16x32_bf16 v[0:3], v[196:199], v[236:239], v[0:3]
	v_mfma_f32_16x16x32_bf16 v[52:55], v[182:185], v[216:219], v[52:55]
	v_mfma_f32_16x16x32_bf16 v[48:51], v[200:203], v[216:219], v[48:51]
	v_mfma_f32_16x16x32_bf16 v[36:39], v[182:185], v[224:227], v[36:39]
	v_mfma_f32_16x16x32_bf16 v[32:35], v[200:203], v[224:227], v[32:35]
	v_mfma_f32_16x16x32_bf16 v[20:23], v[182:185], v[232:235], v[20:23]
	v_mfma_f32_16x16x32_bf16 v[16:19], v[200:203], v[232:235], v[16:19]
	v_mfma_f32_16x16x32_bf16 v[4:7], v[182:185], v[240:243], v[4:7]
	v_mfma_f32_16x16x32_bf16 v[0:3], v[200:203], v[240:243], v[0:3]
	s_barrier
	s_add_i32 s92, s92, 2
	s_add_u32 s36, s36, 0x100
	s_addc_u32 s37, s37, 0
	s_cmp_gt_u32 s92, 13
	s_cbranch_scc0 .LBB0_441
	s_setprio 0
	s_and_saveexec_b64 s[8:9], s[42:43]
	s_cbranch_execz .LBB0_444
	s_barrier

; #define WAIT_V(n) asm volatile("s_waitcnt vmcnt(" #n ")" ::: "memory")
; #define WAIT_L(n) asm volatile("s_waitcnt lgkmcnt(" #n ")" ::: "memory")
; #define BAR __builtin_amdgcn_s_barrier()
; #define SCHED __builtin_amdgcn_sched_barrier(0)
; #define STG_A(b, h, ptr) do { const char* _g = (ptr) + (h) * ahalf; LAS unsigned char* _l = lw + ((b) * 2 + (h)) * 16384; GLDS(_g + voa0, _l); GLDS(_g + voa1, _l + 8192); } while (0)
; #define STG_B(b, h, ptr) do { const char* _g = (ptr) + (h) * bhalf; LAS unsigned char* _l = lw + 65536 + ((b) * 2 + (h)) * 16384; GLDS(_g + vob0, _l); GLDS(_g + vob1, _l + 8192); } while (0)
; #define LDA(dst, b, h) _Pragma("unroll") for (int m = 0; m < 4; ++m) _Pragma("unroll") for (int k = 0; k < 2; ++k) dst[m][k] = *(const LAS bf16x8*)(la + ((b) * 2 + (h)) * 16384 + m * 2048 + k * 1024)
; #define LDB(dst, b, h) _Pragma("unroll") for (int n = 0; n < 2; ++n) _Pragma("unroll") for (int k = 0; k < 2; ++k) dst[n][k] = *(const LAS bf16x8*)(lb + ((b) * 2 + (h)) * 16384 + n * 2048 + k * 1024)
; #define MMA(ai, bj, Af, Bf) do { __builtin_amdgcn_s_setprio(1); \
;     _Pragma("unroll") for (int m = 0; m < 4; ++m) _Pragma("unroll") for (int n = 0; n < 2; ++n) _Pragma("unroll") for (int k = 0; k < 2; ++k) \
;         acc[ai][bj][m][n] = __builtin_amdgcn_mfma_f32_16x16x32_bf16(Bf[n][k], Af[m][k], acc[ai][bj][m][n], 0, 0, 0); \
;     __builtin_amdgcn_s_setprio(0); } while (0)
; template <int BMODE, class Epi, class TileFn>
; DEV void gemm_loop(LAS unsigned char* lds, const bf16_t* __restrict__ A, int lda, const bf16_t* __restrict__ B, int ldb, int K, const Epi& epi, int t0, int tstep, int tend, const TileFn& tf) {
;     ...
;         for (int t = 0; t < nt; t += 2) {
;             const bool last = (t == nt - 2);
;             const char* a1 = cA + (size_t)(t + 1) * 128;
;             const char* a2 = last ? nA : cA + (size_t)(t + 2) * 128;
;             const char* b2 = last ? nB : cB + (size_t)(t + 2) * bks;
;             const char* a3 = a2 + 128; const char* b3 = b2 + bks;
;             LDB(B0, 0, 0); LDB(B1, 0, 1); SCHED; LDA(At, 0, 0); STG_A(1, 1, a1);
;             WAIT_V(8); WAIT_L(0); BAR; MMA(0, 0, At, B0); MMA(0, 1, At, B1); BAR; SCHED;
;             LDA(At, 0, 1); STG_B(0, 0, b2); STG_B(0, 1, b2); STG_A(0, 0, a2);
;             WAIT_V(8); WAIT_L(0); BAR; MMA(1, 0, At, B0); MMA(1, 1, At, B1); BAR; SCHED;
.Lsp_1239:
	ds_read_b128 v[132:135], v225
	ds_read_b128 v[136:139], v225 offset:1024
	ds_read_b128 v[140:143], v225 offset:2048
	ds_read_b128 v[144:147], v225 offset:3072
	ds_read_b128 v[148:151], v225 offset:16384
	ds_read_b128 v[152:155], v225 offset:17408
	ds_read_b128 v[156:159], v225 offset:18432
	ds_read_b128 v[160:163], v225 offset:19456
	s_add_u32 s8, s49, s0
	s_addc_u32 s9, s50, s1
	s_add_u32 s8, s8, 0x18466100
	s_addc_u32 s9, s9, 0
	s_add_u32 s31, s53, s0
	s_addc_u32 s82, s80, s1
	s_cmpk_eq_i32 s0, 0x700
	s_cselect_b32 s77, s29, s9
	s_cselect_b32 s76, s28, s8
	s_cselect_b32 s9, s37, s82
	s_cselect_b32 s8, s30, s31
	v_add_u32_e32 v194, 0xc000, v211
	v_lshl_add_u64 v[204:205], v[120:121], 0, s[0:1]
	v_readfirstlane_b32 s31, v194
	v_add_u32_e32 v194, 0xe000, v211
	s_mov_b32 m0, s31
	v_readfirstlane_b32 s31, v194
	ds_read_b128 v[164:167], v226
	ds_read_b128 v[168:171], v226 offset:1024
	ds_read_b128 v[172:175], v226 offset:2048
	ds_read_b128 v[176:179], v226 offset:3072
	ds_read_b128 v[180:183], v226 offset:4096
	ds_read_b128 v[228:231], v226 offset:5120
	ds_read_b128 v[232:235], v226 offset:6144
	ds_read_b128 v[236:239], v226 offset:7168
	global_load_lds_dwordx4 v[204:205], off
	v_lshl_add_u64 v[204:205], v[122:123], 0, s[0:1]
	s_mov_b32 m0, s31
	s_nop 0
	global_load_lds_dwordx4 v[204:205], off
	s_waitcnt vmcnt(8)
	s_waitcnt lgkmcnt(0)
	s_barrier
	v_mfma_f32_16x16x32_bf16 v[128:131], v[132:135], v[164:167], 0
	v_mfma_f32_16x16x32_bf16 v[124:127], v[140:143], v[164:167], 0
	v_mfma_f32_16x16x32_bf16 v[108:111], v[132:135], v[172:175], 0
	v_mfma_f32_16x16x32_bf16 v[104:107], v[140:143], v[172:175], 0
	v_mfma_f32_16x16x32_bf16 v[92:95], v[132:135], v[180:183], 0
	v_mfma_f32_16x16x32_bf16 v[88:91], v[140:143], v[180:183], 0
	v_mfma_f32_16x16x32_bf16 v[76:79], v[132:135], v[232:235], 0
	v_mfma_f32_16x16x32_bf16 v[72:75], v[140:143], v[232:235], 0
	v_mfma_f32_16x16x32_bf16 v[128:131], v[136:139], v[168:171], v[128:131]
	v_mfma_f32_16x16x32_bf16 v[124:127], v[144:147], v[168:171], v[124:127]
	v_mfma_f32_16x16x32_bf16 v[108:111], v[136:139], v[176:179], v[108:111]
	v_mfma_f32_16x16x32_bf16 v[104:107], v[144:147], v[176:179], v[104:107]
	v_mfma_f32_16x16x32_bf16 v[92:95], v[136:139], v[228:231], v[92:95]
	v_mfma_f32_16x16x32_bf16 v[88:91], v[144:147], v[228:231], v[88:91]
	v_mfma_f32_16x16x32_bf16 v[76:79], v[136:139], v[236:239], v[76:79]
	v_mfma_f32_16x16x32_bf16 v[72:75], v[144:147], v[236:239], v[72:75]
	v_mfma_f32_16x16x32_bf16 v[116:119], v[148:151], v[164:167], 0
	v_mfma_f32_16x16x32_bf16 v[112:115], v[156:159], v[164:167], 0
	v_mfma_f32_16x16x32_bf16 v[100:103], v[148:151], v[172:175], 0
	v_mfma_f32_16x16x32_bf16 v[96:99], v[156:159], v[172:175], 0
	v_mfma_f32_16x16x32_bf16 v[84:87], v[148:151], v[180:183], 0
	v_mfma_f32_16x16x32_bf16 v[80:83], v[156:159], v[180:183], 0
	v_mfma_f32_16x16x32_bf16 v[68:71], v[148:151], v[232:235], 0
	v_mfma_f32_16x16x32_bf16 v[64:67], v[156:159], v[232:235], 0
	v_mfma_f32_16x16x32_bf16 v[116:119], v[152:155], v[168:171], v[116:119]
	v_mfma_f32_16x16x32_bf16 v[112:115], v[160:163], v[168:171], v[112:115]
	v_mfma_f32_16x16x32_bf16 v[100:103], v[152:155], v[176:179], v[100:103]
	v_mfma_f32_16x16x32_bf16 v[96:99], v[160:163], v[176:179], v[96:99]
	v_mfma_f32_16x16x32_bf16 v[84:87], v[152:155], v[228:231], v[84:87]
	v_mfma_f32_16x16x32_bf16 v[80:83], v[160:163], v[228:231], v[80:83]
	v_mfma_f32_16x16x32_bf16 v[68:71], v[152:155], v[236:239], v[68:71]
	v_mfma_f32_16x16x32_bf16 v[64:67], v[160:163], v[236:239], v[64:67]
	s_barrier
	v_readfirstlane_b32 s31, v212
	v_lshl_add_u64 v[204:205], s[8:9], 0, v[196:197]
	s_mov_b32 m0, s31
	v_readfirstlane_b32 s31, v213
	s_add_u32 s82, s8, 0x40000
	ds_read_b128 v[164:167], v226 offset:16384
	ds_read_b128 v[168:171], v226 offset:17408
	ds_read_b128 v[172:175], v226 offset:18432
	ds_read_b128 v[176:179], v226 offset:19456
	ds_read_b128 v[180:183], v226 offset:20480
	ds_read_b128 v[228:231], v226 offset:21504
	ds_read_b128 v[232:235], v226 offset:22528
	ds_read_b128 v[236:239], v226 offset:23552
	global_load_lds_dwordx4 v[204:205], off
	v_lshl_add_u64 v[240:241], s[8:9], 0, v[198:199]
	s_mov_b32 m0, s31
	s_addc_u32 s83, s9, 0
	v_readfirstlane_b32 s31, v214
	global_load_lds_dwordx4 v[240:241], off
	v_lshl_add_u64 v[242:243], s[82:83], 0, v[196:197]
	s_mov_b32 m0, s31
	v_readfirstlane_b32 s31, v215
	global_load_lds_dwordx4 v[242:243], off
	v_lshl_add_u64 v[242:243], s[82:83], 0, v[198:199]
	s_mov_b32 m0, s31
	v_readfirstlane_b32 s31, v211
	global_load_lds_dwordx4 v[242:243], off
	v_lshl_add_u64 v[242:243], s[76:77], 0, v[184:185]
	s_mov_b32 m0, s31
	v_readfirstlane_b32 s31, v216
	global_load_lds_dwordx4 v[242:243], off
	v_lshl_add_u64 v[244:245], s[76:77], 0, v[186:187]
	s_mov_b32 m0, s31
	s_nop 0
	global_load_lds_dwordx4 v[244:245], off
	s_waitcnt vmcnt(8)
	s_waitcnt lgkmcnt(0)
	s_barrier
	v_mfma_f32_16x16x32_bf16 v[60:63], v[132:135], v[164:167], 0
	v_mfma_f32_16x16x32_bf16 v[56:59], v[140:143], v[164:167], 0
	v_mfma_f32_16x16x32_bf16 v[44:47], v[132:135], v[172:175], 0
	v_mfma_f32_16x16x32_bf16 v[40:43], v[140:143], v[172:175], 0
	v_mfma_f32_16x16x32_bf16 v[28:31], v[132:135], v[180:183], 0
	v_mfma_f32_16x16x32_bf16 v[24:27], v[140:143], v[180:183], 0
	v_mfma_f32_16x16x32_bf16 v[12:15], v[132:135], v[232:235], 0
	v_mfma_f32_16x16x32_bf16 v[8:11], v[140:143], v[232:235], 0
	v_mfma_f32_16x16x32_bf16 v[60:63], v[136:139], v[168:171], v[60:63]
	v_mfma_f32_16x16x32_bf16 v[56:59], v[144:147], v[168:171], v[56:59]
	v_mfma_f32_16x16x32_bf16 v[44:47], v[136:139], v[176:179], v[44:47]
	v_mfma_f32_16x16x32_bf16 v[40:43], v[144:147], v[176:179], v[40:43]
	v_mfma_f32_16x16x32_bf16 v[28:31], v[136:139], v[228:231], v[28:31]
	v_mfma_f32_16x16x32_bf16 v[24:27], v[144:147], v[228:231], v[24:27]
	v_mfma_f32_16x16x32_bf16 v[12:15], v[136:139], v[236:239], v[12:15]
	v_mfma_f32_16x16x32_bf16 v[8:11], v[144:147], v[236:239], v[8:11]
	v_mfma_f32_16x16x32_bf16 v[52:55], v[148:151], v[164:167], 0
	v_mfma_f32_16x16x32_bf16 v[48:51], v[156:159], v[164:167], 0
	v_mfma_f32_16x16x32_bf16 v[36:39], v[148:151], v[172:175], 0
	v_mfma_f32_16x16x32_bf16 v[32:35], v[156:159], v[172:175], 0
	v_mfma_f32_16x16x32_bf16 v[20:23], v[148:151], v[180:183], 0
	v_mfma_f32_16x16x32_bf16 v[16:19], v[156:159], v[180:183], 0
	v_mfma_f32_16x16x32_bf16 v[4:7], v[148:151], v[232:235], 0
	v_mfma_f32_16x16x32_bf16 v[0:3], v[156:159], v[232:235], 0
	v_mfma_f32_16x16x32_bf16 v[52:55], v[152:155], v[168:171], v[52:55]
	v_mfma_f32_16x16x32_bf16 v[48:51], v[160:163], v[168:171], v[48:51]
	v_mfma_f32_16x16x32_bf16 v[36:39], v[152:155], v[176:179], v[36:39]
	v_mfma_f32_16x16x32_bf16 v[32:35], v[160:163], v[176:179], v[32:35]
	v_mfma_f32_16x16x32_bf16 v[20:23], v[152:155], v[228:231], v[20:23]
	v_mfma_f32_16x16x32_bf16 v[16:19], v[160:163], v[228:231], v[16:19]
	v_mfma_f32_16x16x32_bf16 v[4:7], v[152:155], v[236:239], v[4:7]
	v_mfma_f32_16x16x32_bf16 v[0:3], v[160:163], v[236:239], v[0:3]
	s_barrier
	s_branch .Lkmid_1239
; #define WAIT_V(n) asm volatile("s_waitcnt vmcnt(" #n ")" ::: "memory")
; #define WAIT_L(n) asm volatile("s_waitcnt lgkmcnt(" #n ")" ::: "memory")
; #define BAR __builtin_amdgcn_s_barrier()
; #define SCHED __builtin_amdgcn_sched_barrier(0)
; #define STG_A(b, h, ptr) do { const char* _g = (ptr) + (h) * ahalf; LAS unsigned char* _l = lw + ((b) * 2 + (h)) * 16384; GLDS(_g + voa0, _l); GLDS(_g + voa1, _l + 8192); } while (0)
; #define STG_B(b, h, ptr) do { const char* _g = (ptr) + (h) * bhalf; LAS unsigned char* _l = lw + 65536 + ((b) * 2 + (h)) * 16384; GLDS(_g + vob0, _l); GLDS(_g + vob1, _l + 8192); } while (0)
; #define LDA(dst, b, h) _Pragma("unroll") for (int m = 0; m < 4; ++m) _Pragma("unroll") for (int k = 0; k < 2; ++k) dst[m][k] = *(const LAS bf16x8*)(la + ((b) * 2 + (h)) * 16384 + m * 2048 + k * 1024)
; #define LDB(dst, b, h) _Pragma("unroll") for (int n = 0; n < 2; ++n) _Pragma("unroll") for (int k = 0; k < 2; ++k) dst[n][k] = *(const LAS bf16x8*)(lb + ((b) * 2 + (h)) * 16384 + n * 2048 + k * 1024)
; #define MMA(ai, bj, Af, Bf) do { __builtin_amdgcn_s_setprio(1); \
;     _Pragma("unroll") for (int m = 0; m < 4; ++m) _Pragma("unroll") for (int n = 0; n < 2; ++n) _Pragma("unroll") for (int k = 0; k < 2; ++k) \
;         acc[ai][bj][m][n] = __builtin_amdgcn_mfma_f32_16x16x32_bf16(Bf[n][k], Af[m][k], acc[ai][bj][m][n], 0, 0, 0); \
;     __builtin_amdgcn_s_setprio(0); } while (0)
; template <int BMODE, class Epi, class TileFn>
; DEV void gemm_loop(LAS unsigned char* lds, const bf16_t* __restrict__ A, int lda, const bf16_t* __restrict__ B, int ldb, int K, const Epi& epi, int t0, int tstep, int tend, const TileFn& tf) {
;     ...
;         for (int t = 0; t < nt; t += 2) {
;             const bool last = (t == nt - 2);
;             const char* a1 = cA + (size_t)(t + 1) * 128;
;             const char* a2 = last ? nA : cA + (size_t)(t + 2) * 128;
;             const char* b2 = last ? nB : cB + (size_t)(t + 2) * bks;
;             const char* a3 = a2 + 128; const char* b3 = b2 + bks;
;             LDB(B0, 0, 0); LDB(B1, 0, 1); SCHED; LDA(At, 0, 0); STG_A(1, 1, a1);
;             WAIT_V(8); WAIT_L(0); BAR; MMA(0, 0, At, B0); MMA(0, 1, At, B1); BAR; SCHED;
;             LDA(At, 0, 1); STG_B(0, 0, b2); STG_B(0, 1, b2); STG_A(0, 0, a2);
;             WAIT_V(8); WAIT_L(0); BAR; MMA(1, 0, At, B0); MMA(1, 1, At, B1); BAR; SCHED;
.LBB0_1239:
	ds_read_b128 v[132:135], v225
	ds_read_b128 v[136:139], v225 offset:1024
	ds_read_b128 v[140:143], v225 offset:2048
	ds_read_b128 v[144:147], v225 offset:3072
	ds_read_b128 v[148:151], v225 offset:16384
	ds_read_b128 v[152:155], v225 offset:17408
	ds_read_b128 v[156:159], v225 offset:18432
	ds_read_b128 v[160:163], v225 offset:19456
	s_add_u32 s8, s49, s0
	s_addc_u32 s9, s50, s1
	s_add_u32 s8, s8, 0x18466100
	s_addc_u32 s9, s9, 0
	s_add_u32 s31, s53, s0
	s_addc_u32 s82, s80, s1
	s_cmpk_eq_i32 s0, 0x700
	s_cselect_b32 s77, s29, s9
	s_cselect_b32 s76, s28, s8
	s_cselect_b32 s9, s37, s82
	s_cselect_b32 s8, s30, s31
	v_add_u32_e32 v194, 0xc000, v211
	v_lshl_add_u64 v[204:205], v[120:121], 0, s[0:1]
	v_readfirstlane_b32 s31, v194
	v_add_u32_e32 v194, 0xe000, v211
	s_mov_b32 m0, s31
	v_readfirstlane_b32 s31, v194
	ds_read_b128 v[164:167], v226
	ds_read_b128 v[168:171], v226 offset:1024
	ds_read_b128 v[172:175], v226 offset:2048
	ds_read_b128 v[176:179], v226 offset:3072
	ds_read_b128 v[180:183], v226 offset:4096
	ds_read_b128 v[228:231], v226 offset:5120
	ds_read_b128 v[232:235], v226 offset:6144
	ds_read_b128 v[236:239], v226 offset:7168
	global_load_lds_dwordx4 v[204:205], off
	v_lshl_add_u64 v[204:205], v[122:123], 0, s[0:1]
	s_mov_b32 m0, s31
	s_nop 0
	global_load_lds_dwordx4 v[204:205], off
	s_waitcnt vmcnt(8)
	s_waitcnt lgkmcnt(0)
	s_barrier
	v_mfma_f32_16x16x32_bf16 v[128:131], v[132:135], v[164:167], v[128:131]
	v_mfma_f32_16x16x32_bf16 v[124:127], v[140:143], v[164:167], v[124:127]
	v_mfma_f32_16x16x32_bf16 v[108:111], v[132:135], v[172:175], v[108:111]
	v_mfma_f32_16x16x32_bf16 v[104:107], v[140:143], v[172:175], v[104:107]
	v_mfma_f32_16x16x32_bf16 v[92:95], v[132:135], v[180:183], v[92:95]
	v_mfma_f32_16x16x32_bf16 v[88:91], v[140:143], v[180:183], v[88:91]
	v_mfma_f32_16x16x32_bf16 v[76:79], v[132:135], v[232:235], v[76:79]
	v_mfma_f32_16x16x32_bf16 v[72:75], v[140:143], v[232:235], v[72:75]
	v_mfma_f32_16x16x32_bf16 v[128:131], v[136:139], v[168:171], v[128:131]
	v_mfma_f32_16x16x32_bf16 v[124:127], v[144:147], v[168:171], v[124:127]
	v_mfma_f32_16x16x32_bf16 v[108:111], v[136:139], v[176:179], v[108:111]
	v_mfma_f32_16x16x32_bf16 v[104:107], v[144:147], v[176:179], v[104:107]
	v_mfma_f32_16x16x32_bf16 v[92:95], v[136:139], v[228:231], v[92:95]
	v_mfma_f32_16x16x32_bf16 v[88:91], v[144:147], v[228:231], v[88:91]
	v_mfma_f32_16x16x32_bf16 v[76:79], v[136:139], v[236:239], v[76:79]
	v_mfma_f32_16x16x32_bf16 v[72:75], v[144:147], v[236:239], v[72:75]
	v_mfma_f32_16x16x32_bf16 v[116:119], v[148:151], v[164:167], v[116:119]
	v_mfma_f32_16x16x32_bf16 v[112:115], v[156:159], v[164:167], v[112:115]
	v_mfma_f32_16x16x32_bf16 v[100:103], v[148:151], v[172:175], v[100:103]
	v_mfma_f32_16x16x32_bf16 v[96:99], v[156:159], v[172:175], v[96:99]
	v_mfma_f32_16x16x32_bf16 v[84:87], v[148:151], v[180:183], v[84:87]
	v_mfma_f32_16x16x32_bf16 v[80:83], v[156:159], v[180:183], v[80:83]
	v_mfma_f32_16x16x32_bf16 v[68:71], v[148:151], v[232:235], v[68:71]
	v_mfma_f32_16x16x32_bf16 v[64:67], v[156:159], v[232:235], v[64:67]
	v_mfma_f32_16x16x32_bf16 v[116:119], v[152:155], v[168:171], v[116:119]
	v_mfma_f32_16x16x32_bf16 v[112:115], v[160:163], v[168:171], v[112:115]
	v_mfma_f32_16x16x32_bf16 v[100:103], v[152:155], v[176:179], v[100:103]
	v_mfma_f32_16x16x32_bf16 v[96:99], v[160:163], v[176:179], v[96:99]
	v_mfma_f32_16x16x32_bf16 v[84:87], v[152:155], v[228:231], v[84:87]
	v_mfma_f32_16x16x32_bf16 v[80:83], v[160:163], v[228:231], v[80:83]
	v_mfma_f32_16x16x32_bf16 v[68:71], v[152:155], v[236:239], v[68:71]
	v_mfma_f32_16x16x32_bf16 v[64:67], v[160:163], v[236:239], v[64:67]
	s_barrier
	v_readfirstlane_b32 s31, v212
	v_lshl_add_u64 v[204:205], s[8:9], 0, v[196:197]
	s_mov_b32 m0, s31
	v_readfirstlane_b32 s31, v213
	s_add_u32 s82, s8, 0x40000
	ds_read_b128 v[164:167], v226 offset:16384
	ds_read_b128 v[168:171], v226 offset:17408
	ds_read_b128 v[172:175], v226 offset:18432
	ds_read_b128 v[176:179], v226 offset:19456
	ds_read_b128 v[180:183], v226 offset:20480
	ds_read_b128 v[228:231], v226 offset:21504
	ds_read_b128 v[232:235], v226 offset:22528
	ds_read_b128 v[236:239], v226 offset:23552
	global_load_lds_dwordx4 v[204:205], off
	v_lshl_add_u64 v[240:241], s[8:9], 0, v[198:199]
	s_mov_b32 m0, s31
	s_addc_u32 s83, s9, 0
	v_readfirstlane_b32 s31, v214
	global_load_lds_dwordx4 v[240:241], off
	v_lshl_add_u64 v[242:243], s[82:83], 0, v[196:197]
	s_mov_b32 m0, s31
	v_readfirstlane_b32 s31, v215
	global_load_lds_dwordx4 v[242:243], off
	v_lshl_add_u64 v[242:243], s[82:83], 0, v[198:199]
	s_mov_b32 m0, s31
	v_readfirstlane_b32 s31, v211
	global_load_lds_dwordx4 v[242:243], off
	v_lshl_add_u64 v[242:243], s[76:77], 0, v[184:185]
	s_mov_b32 m0, s31
	v_readfirstlane_b32 s31, v216
	global_load_lds_dwordx4 v[242:243], off
	v_lshl_add_u64 v[244:245], s[76:77], 0, v[186:187]
	s_mov_b32 m0, s31
	s_nop 0
	global_load_lds_dwordx4 v[244:245], off
	s_waitcnt vmcnt(8)
	s_waitcnt lgkmcnt(0)
	s_barrier
; #define WAIT_V(n) asm volatile("s_waitcnt vmcnt(" #n ")" ::: "memory")
; #define WAIT_L(n) asm volatile("s_waitcnt lgkmcnt(" #n ")" ::: "memory")
; #define BAR __builtin_amdgcn_s_barrier()
; #define SCHED __builtin_amdgcn_sched_barrier(0)
; #define STG_A(b, h, ptr) do { const char* _g = (ptr) + (h) * ahalf; LAS unsigned char* _l = lw + ((b) * 2 + (h)) * 16384; GLDS(_g + voa0, _l); GLDS(_g + voa1, _l + 8192); } while (0)
; #define LDA(dst, b, h) _Pragma("unroll") for (int m = 0; m < 4; ++m) _Pragma("unroll") for (int k = 0; k < 2; ++k) dst[m][k] = *(const LAS bf16x8*)(la + ((b) * 2 + (h)) * 16384 + m * 2048 + k * 1024)
; #define LDB(dst, b, h) _Pragma("unroll") for (int n = 0; n < 2; ++n) _Pragma("unroll") for (int k = 0; k < 2; ++k) dst[n][k] = *(const LAS bf16x8*)(lb + ((b) * 2 + (h)) * 16384 + n * 2048 + k * 1024)
; #define MMA(ai, bj, Af, Bf) do { __builtin_amdgcn_s_setprio(1); \
;     _Pragma("unroll") for (int m = 0; m < 4; ++m) _Pragma("unroll") for (int n = 0; n < 2; ++n) _Pragma("unroll") for (int k = 0; k < 2; ++k) \
;         acc[ai][bj][m][n] = __builtin_amdgcn_mfma_f32_16x16x32_bf16(Bf[n][k], Af[m][k], acc[ai][bj][m][n], 0, 0, 0); \
;     __builtin_amdgcn_s_setprio(0); } while (0)
; template <int BMODE, class Epi, class TileFn>
; DEV void gemm_loop(LAS unsigned char* lds, const bf16_t* __restrict__ A, int lda, const bf16_t* __restrict__ B, int ldb, int K, const Epi& epi, int t0, int tstep, int tend, const TileFn& tf) {
;     ...
;             WAIT_V(8); WAIT_L(0); BAR; MMA(1, 0, At, B0); MMA(1, 1, At, B1); BAR; SCHED;
;             LDB(B0, 1, 0); LDB(B1, 1, 1); SCHED; LDA(At, 1, 0); STG_A(0, 1, a2);
;             WAIT_V(8); WAIT_L(0); BAR; MMA(0, 0, At, B0); MMA(0, 1, At, B1); BAR; SCHED;
	v_mfma_f32_16x16x32_bf16 v[60:63], v[132:135], v[164:167], v[60:63]
	v_mfma_f32_16x16x32_bf16 v[56:59], v[140:143], v[164:167], v[56:59]
	v_mfma_f32_16x16x32_bf16 v[44:47], v[132:135], v[172:175], v[44:47]
	v_mfma_f32_16x16x32_bf16 v[40:43], v[140:143], v[172:175], v[40:43]
	v_mfma_f32_16x16x32_bf16 v[28:31], v[132:135], v[180:183], v[28:31]
	v_mfma_f32_16x16x32_bf16 v[24:27], v[140:143], v[180:183], v[24:27]
	v_mfma_f32_16x16x32_bf16 v[12:15], v[132:135], v[232:235], v[12:15]
	v_mfma_f32_16x16x32_bf16 v[8:11], v[140:143], v[232:235], v[8:11]
	v_mfma_f32_16x16x32_bf16 v[60:63], v[136:139], v[168:171], v[60:63]
	v_mfma_f32_16x16x32_bf16 v[56:59], v[144:147], v[168:171], v[56:59]
	v_mfma_f32_16x16x32_bf16 v[44:47], v[136:139], v[176:179], v[44:47]
	v_mfma_f32_16x16x32_bf16 v[40:43], v[144:147], v[176:179], v[40:43]
	v_mfma_f32_16x16x32_bf16 v[28:31], v[136:139], v[228:231], v[28:31]
	v_mfma_f32_16x16x32_bf16 v[24:27], v[144:147], v[228:231], v[24:27]
	v_mfma_f32_16x16x32_bf16 v[12:15], v[136:139], v[236:239], v[12:15]
	v_mfma_f32_16x16x32_bf16 v[8:11], v[144:147], v[236:239], v[8:11]
	v_mfma_f32_16x16x32_bf16 v[52:55], v[148:151], v[164:167], v[52:55]
	v_mfma_f32_16x16x32_bf16 v[48:51], v[156:159], v[164:167], v[48:51]
	v_mfma_f32_16x16x32_bf16 v[36:39], v[148:151], v[172:175], v[36:39]
	v_mfma_f32_16x16x32_bf16 v[32:35], v[156:159], v[172:175], v[32:35]
	v_mfma_f32_16x16x32_bf16 v[20:23], v[148:151], v[180:183], v[20:23]
	v_mfma_f32_16x16x32_bf16 v[16:19], v[156:159], v[180:183], v[16:19]
	v_mfma_f32_16x16x32_bf16 v[4:7], v[148:151], v[232:235], v[4:7]
	v_mfma_f32_16x16x32_bf16 v[0:3], v[156:159], v[232:235], v[0:3]
	v_mfma_f32_16x16x32_bf16 v[52:55], v[152:155], v[168:171], v[52:55]
	v_mfma_f32_16x16x32_bf16 v[48:51], v[160:163], v[168:171], v[48:51]
	v_mfma_f32_16x16x32_bf16 v[36:39], v[152:155], v[176:179], v[36:39]
	v_mfma_f32_16x16x32_bf16 v[32:35], v[160:163], v[176:179], v[32:35]
	v_mfma_f32_16x16x32_bf16 v[20:23], v[152:155], v[228:231], v[20:23]
	v_mfma_f32_16x16x32_bf16 v[16:19], v[160:163], v[228:231], v[16:19]
	v_mfma_f32_16x16x32_bf16 v[4:7], v[152:155], v[236:239], v[4:7]
	v_mfma_f32_16x16x32_bf16 v[0:3], v[160:163], v[236:239], v[0:3]
	s_barrier
.Lkmid_1239:
	ds_read_b128 v[132:135], v225 offset:32768
	ds_read_b128 v[136:139], v225 offset:33792
	ds_read_b128 v[140:143], v225 offset:34816
	ds_read_b128 v[144:147], v225 offset:35840
	ds_read_b128 v[148:151], v225 offset:49152
	ds_read_b128 v[152:155], v225 offset:50176
	ds_read_b128 v[156:159], v225 offset:51200
	ds_read_b128 v[160:163], v225 offset:52224
	s_add_u32 s76, s76, 0x40000
	s_addc_u32 s77, s77, 0
	v_readfirstlane_b32 s31, v217
	v_lshl_add_u64 v[246:247], s[76:77], 0, v[184:185]
	s_mov_b32 m0, s31
	v_readfirstlane_b32 s31, v218
	ds_read_b128 v[164:167], v226 offset:32768
	ds_read_b128 v[168:171], v226 offset:33792
	ds_read_b128 v[172:175], v226 offset:34816
	ds_read_b128 v[176:179], v226 offset:35840
	ds_read_b128 v[180:183], v226 offset:36864
	ds_read_b128 v[228:231], v226 offset:37888
	ds_read_b128 v[232:235], v226 offset:38912
	ds_read_b128 v[236:239], v226 offset:39936
	global_load_lds_dwordx4 v[246:247], off
	v_lshl_add_u64 v[246:247], s[76:77], 0, v[186:187]
	s_mov_b32 m0, s31
	s_nop 0
	global_load_lds_dwordx4 v[246:247], off
	s_waitcnt vmcnt(8)
	s_waitcnt lgkmcnt(0)
	s_barrier
	v_mfma_f32_16x16x32_bf16 v[128:131], v[132:135], v[164:167], v[128:131]
	v_mfma_f32_16x16x32_bf16 v[124:127], v[140:143], v[164:167], v[124:127]
	v_mfma_f32_16x16x32_bf16 v[108:111], v[132:135], v[172:175], v[108:111]
	v_mfma_f32_16x16x32_bf16 v[104:107], v[140:143], v[172:175], v[104:107]
	v_mfma_f32_16x16x32_bf16 v[92:95], v[132:135], v[180:183], v[92:95]
	v_mfma_f32_16x16x32_bf16 v[88:91], v[140:143], v[180:183], v[88:91]
	v_mfma_f32_16x16x32_bf16 v[76:79], v[132:135], v[232:235], v[76:79]
	v_mfma_f32_16x16x32_bf16 v[72:75], v[140:143], v[232:235], v[72:75]
	v_mfma_f32_16x16x32_bf16 v[128:131], v[136:139], v[168:171], v[128:131]
	v_mfma_f32_16x16x32_bf16 v[124:127], v[144:147], v[168:171], v[124:127]
	v_mfma_f32_16x16x32_bf16 v[108:111], v[136:139], v[176:179], v[108:111]
	v_mfma_f32_16x16x32_bf16 v[104:107], v[144:147], v[176:179], v[104:107]
	v_mfma_f32_16x16x32_bf16 v[92:95], v[136:139], v[228:231], v[92:95]
	v_mfma_f32_16x16x32_bf16 v[88:91], v[144:147], v[228:231], v[88:91]
	v_mfma_f32_16x16x32_bf16 v[76:79], v[136:139], v[236:239], v[76:79]
	v_mfma_f32_16x16x32_bf16 v[72:75], v[144:147], v[236:239], v[72:75]
	v_mfma_f32_16x16x32_bf16 v[116:119], v[148:151], v[164:167], v[116:119]
	v_mfma_f32_16x16x32_bf16 v[112:115], v[156:159], v[164:167], v[112:115]
	v_mfma_f32_16x16x32_bf16 v[100:103], v[148:151], v[172:175], v[100:103]
	v_mfma_f32_16x16x32_bf16 v[96:99], v[156:159], v[172:175], v[96:99]
	v_mfma_f32_16x16x32_bf16 v[84:87], v[148:151], v[180:183], v[84:87]
	v_mfma_f32_16x16x32_bf16 v[80:83], v[156:159], v[180:183], v[80:83]
	v_mfma_f32_16x16x32_bf16 v[68:71], v[148:151], v[232:235], v[68:71]
	v_mfma_f32_16x16x32_bf16 v[64:67], v[156:159], v[232:235], v[64:67]
	v_mfma_f32_16x16x32_bf16 v[116:119], v[152:155], v[168:171], v[116:119]
	v_mfma_f32_16x16x32_bf16 v[112:115], v[160:163], v[168:171], v[112:115]
	v_mfma_f32_16x16x32_bf16 v[100:103], v[152:155], v[176:179], v[100:103]
	v_mfma_f32_16x16x32_bf16 v[96:99], v[160:163], v[176:179], v[96:99]
	v_mfma_f32_16x16x32_bf16 v[84:87], v[152:155], v[228:231], v[84:87]
	v_mfma_f32_16x16x32_bf16 v[80:83], v[160:163], v[228:231], v[80:83]
	v_mfma_f32_16x16x32_bf16 v[68:71], v[152:155], v[236:239], v[68:71]
	v_mfma_f32_16x16x32_bf16 v[64:67], v[160:163], v[236:239], v[64:67]
	s_barrier
; #define WAIT_V(n) asm volatile("s_waitcnt vmcnt(" #n ")" ::: "memory")
; #define WAIT_L(n) asm volatile("s_waitcnt lgkmcnt(" #n ")" ::: "memory")
; #define BAR __builtin_amdgcn_s_barrier()
; #define SCHED __builtin_amdgcn_sched_barrier(0)
; #define STG_A(b, h, ptr) do { const char* _g = (ptr) + (h) * ahalf; LAS unsigned char* _l = lw + ((b) * 2 + (h)) * 16384; GLDS(_g + voa0, _l); GLDS(_g + voa1, _l + 8192); } while (0)
; #define STG_B(b, h, ptr) do { const char* _g = (ptr) + (h) * bhalf; LAS unsigned char* _l = lw + 65536 + ((b) * 2 + (h)) * 16384; GLDS(_g + vob0, _l); GLDS(_g + vob1, _l + 8192); } while (0)
; #define LDA(dst, b, h) _Pragma("unroll") for (int m = 0; m < 4; ++m) _Pragma("unroll") for (int k = 0; k < 2; ++k) dst[m][k] = *(const LAS bf16x8*)(la + ((b) * 2 + (h)) * 16384 + m * 2048 + k * 1024)
; #define MMA(ai, bj, Af, Bf) do { __builtin_amdgcn_s_setprio(1); \
;     _Pragma("unroll") for (int m = 0; m < 4; ++m) _Pragma("unroll") for (int n = 0; n < 2; ++n) _Pragma("unroll") for (int k = 0; k < 2; ++k) \
;         acc[ai][bj][m][n] = __builtin_amdgcn_mfma_f32_16x16x32_bf16(Bf[n][k], Af[m][k], acc[ai][bj][m][n], 0, 0, 0); \
;     __builtin_amdgcn_s_setprio(0); } while (0)
; template <int BMODE, class Epi, class TileFn>
; DEV void gemm_loop(LAS unsigned char* lds, const bf16_t* __restrict__ A, int lda, const bf16_t* __restrict__ B, int ldb, int K, const Epi& epi, int t0, int tstep, int tend, const TileFn& tf) {
;     ...
;             LDA(At, 1, 1); STG_B(1, 0, b3); STG_B(1, 1, b3); STG_A(1, 0, a3);
;             WAIT_V(8); WAIT_L(0); BAR; MMA(1, 0, At, B0); MMA(1, 1, At, B1); BAR; SCHED;
;         }
;         if (wr == 0) BAR;
	v_readfirstlane_b32 s31, v219
	v_lshl_add_u64 v[204:205], v[204:205], 0, s[2:3]
	s_mov_b32 m0, s31
	v_readfirstlane_b32 s31, v220
	s_add_u32 s8, s8, 0x40080
	ds_read_b128 v[164:167], v226 offset:49152
	ds_read_b128 v[168:171], v226 offset:50176
	ds_read_b128 v[172:175], v226 offset:51200
	ds_read_b128 v[176:179], v226 offset:52224
	ds_read_b128 v[180:183], v226 offset:53248
	ds_read_b128 v[228:231], v226 offset:54272
	ds_read_b128 v[232:235], v226 offset:55296
	ds_read_b128 v[236:239], v226 offset:56320
	global_load_lds_dwordx4 v[204:205], off
	v_lshl_add_u64 v[204:205], v[240:241], 0, s[2:3]
	s_mov_b32 m0, s31
	s_addc_u32 s9, s9, 0
	v_readfirstlane_b32 s31, v223
	global_load_lds_dwordx4 v[204:205], off
	v_lshl_add_u64 v[204:205], s[8:9], 0, v[196:197]
	s_mov_b32 m0, s31
	s_nop 0
	global_load_lds_dwordx4 v[204:205], off
	v_lshl_add_u64 v[204:205], s[8:9], 0, v[198:199]
	v_readfirstlane_b32 s8, v224
	s_mov_b32 m0, s8
	v_readfirstlane_b32 s8, v221
	global_load_lds_dwordx4 v[204:205], off
	v_lshl_add_u64 v[204:205], v[242:243], 0, s[2:3]
	s_mov_b32 m0, s8
	v_readfirstlane_b32 s8, v222
	global_load_lds_dwordx4 v[204:205], off
	v_lshl_add_u64 v[204:205], v[244:245], 0, s[2:3]
	s_mov_b32 m0, s8
	s_nop 0
	global_load_lds_dwordx4 v[204:205], off
	s_waitcnt vmcnt(8)
	s_waitcnt lgkmcnt(0)
	s_barrier
	v_mfma_f32_16x16x32_bf16 v[60:63], v[132:135], v[164:167], v[60:63]
	v_mfma_f32_16x16x32_bf16 v[56:59], v[140:143], v[164:167], v[56:59]
	v_mfma_f32_16x16x32_bf16 v[44:47], v[132:135], v[172:175], v[44:47]
	v_mfma_f32_16x16x32_bf16 v[40:43], v[140:143], v[172:175], v[40:43]
	v_mfma_f32_16x16x32_bf16 v[28:31], v[132:135], v[180:183], v[28:31]
	v_mfma_f32_16x16x32_bf16 v[24:27], v[140:143], v[180:183], v[24:27]
	v_mfma_f32_16x16x32_bf16 v[12:15], v[132:135], v[232:235], v[12:15]
	v_mfma_f32_16x16x32_bf16 v[8:11], v[140:143], v[232:235], v[8:11]
	v_mfma_f32_16x16x32_bf16 v[60:63], v[136:139], v[168:171], v[60:63]
	v_mfma_f32_16x16x32_bf16 v[56:59], v[144:147], v[168:171], v[56:59]
	v_mfma_f32_16x16x32_bf16 v[44:47], v[136:139], v[176:179], v[44:47]
	v_mfma_f32_16x16x32_bf16 v[40:43], v[144:147], v[176:179], v[40:43]
	v_mfma_f32_16x16x32_bf16 v[28:31], v[136:139], v[228:231], v[28:31]
	v_mfma_f32_16x16x32_bf16 v[24:27], v[144:147], v[228:231], v[24:27]
	v_mfma_f32_16x16x32_bf16 v[12:15], v[136:139], v[236:239], v[12:15]
	v_mfma_f32_16x16x32_bf16 v[8:11], v[144:147], v[236:239], v[8:11]
	v_mfma_f32_16x16x32_bf16 v[52:55], v[148:151], v[164:167], v[52:55]
	v_mfma_f32_16x16x32_bf16 v[48:51], v[156:159], v[164:167], v[48:51]
	v_mfma_f32_16x16x32_bf16 v[36:39], v[148:151], v[172:175], v[36:39]
	v_mfma_f32_16x16x32_bf16 v[32:35], v[156:159], v[172:175], v[32:35]
	v_mfma_f32_16x16x32_bf16 v[20:23], v[148:151], v[180:183], v[20:23]
	v_mfma_f32_16x16x32_bf16 v[16:19], v[156:159], v[180:183], v[16:19]
	v_mfma_f32_16x16x32_bf16 v[4:7], v[148:151], v[232:235], v[4:7]
	v_mfma_f32_16x16x32_bf16 v[0:3], v[156:159], v[232:235], v[0:3]
	v_mfma_f32_16x16x32_bf16 v[52:55], v[152:155], v[168:171], v[52:55]
	v_mfma_f32_16x16x32_bf16 v[48:51], v[160:163], v[168:171], v[48:51]
	v_mfma_f32_16x16x32_bf16 v[36:39], v[152:155], v[176:179], v[36:39]
	v_mfma_f32_16x16x32_bf16 v[32:35], v[160:163], v[176:179], v[32:35]
	v_mfma_f32_16x16x32_bf16 v[20:23], v[152:155], v[228:231], v[20:23]
	v_mfma_f32_16x16x32_bf16 v[16:19], v[160:163], v[228:231], v[16:19]
	v_mfma_f32_16x16x32_bf16 v[4:7], v[152:155], v[236:239], v[4:7]
	v_mfma_f32_16x16x32_bf16 v[0:3], v[160:163], v[236:239], v[0:3]
	s_barrier
	s_add_i32 s81, s81, 2
	s_add_u32 s0, s0, 0x100
	s_addc_u32 s1, s1, 0
	s_cmp_gt_u32 s81, 13
	s_cbranch_scc0 .LBB0_1239
	s_setprio 0
	s_and_saveexec_b64 s[0:1], s[44:45]
	s_cbranch_execz .LBB0_1242
	s_barrier

; #define WAIT_V(n) asm volatile("s_waitcnt vmcnt(" #n ")" ::: "memory")
; #define WAIT_L(n) asm volatile("s_waitcnt lgkmcnt(" #n ")" ::: "memory")
; #define BAR __builtin_amdgcn_s_barrier()
; #define SCHED __builtin_amdgcn_sched_barrier(0)
; #define STG_A(b, h, ptr) do { const char* _g = (ptr) + (h) * ahalf; LAS unsigned char* _l = lw + ((b) * 2 + (h)) * 16384; GLDS(_g + voa0, _l); GLDS(_g + voa1, _l + 8192); } while (0)
; #define STG_B(b, h, ptr) do { const char* _g = (ptr) + (h) * bhalf; LAS unsigned char* _l = lw + 65536 + ((b) * 2 + (h)) * 16384; GLDS(_g + vob0, _l); GLDS(_g + vob1, _l + 8192); } while (0)
; #define LDA(dst, b, h) _Pragma("unroll") for (int m = 0; m < 4; ++m) _Pragma("unroll") for (int k = 0; k < 2; ++k) dst[m][k] = *(const LAS bf16x8*)(la + ((b) * 2 + (h)) * 16384 + m * 2048 + k * 1024)
; #define LDB(dst, b, h) _Pragma("unroll") for (int n = 0; n < 2; ++n) _Pragma("unroll") for (int k = 0; k < 2; ++k) dst[n][k] = *(const LAS bf16x8*)(lb + ((b) * 2 + (h)) * 16384 + n * 2048 + k * 1024)
; #define MMA(ai, bj, Af, Bf) do { __builtin_amdgcn_s_setprio(1); \
;     _Pragma("unroll") for (int m = 0; m < 4; ++m) _Pragma("unroll") for (int n = 0; n < 2; ++n) _Pragma("unroll") for (int k = 0; k < 2; ++k) \
;         acc[ai][bj][m][n] = __builtin_amdgcn_mfma_f32_16x16x32_bf16(Bf[n][k], Af[m][k], acc[ai][bj][m][n], 0, 0, 0); \
;     __builtin_amdgcn_s_setprio(0); } while (0)
; template <int BMODE, class Epi, class TileFn>
; DEV void gemm_loop(LAS unsigned char* lds, const bf16_t* __restrict__ A, int lda, const bf16_t* __restrict__ B, int ldb, int K, const Epi& epi, int t0, int tstep, int tend, const TileFn& tf) {
;     ...
;         for (int t = 0; t < nt; t += 2) {
;             const bool last = (t == nt - 2);
;             const char* a1 = cA + (size_t)(t + 1) * 128;
;             const char* a2 = last ? nA : cA + (size_t)(t + 2) * 128;
;             const char* b2 = last ? nB : cB + (size_t)(t + 2) * bks;
;             const char* a3 = a2 + 128; const char* b3 = b2 + bks;
;             LDB(B0, 0, 0); LDB(B1, 0, 1); SCHED; LDA(At, 0, 0); STG_A(1, 1, a1);
;             WAIT_V(8); WAIT_L(0); BAR; MMA(0, 0, At, B0); MMA(0, 1, At, B1); BAR; SCHED;
;             LDA(At, 0, 1); STG_B(0, 0, b2); STG_B(0, 1, b2); STG_A(0, 0, a2);
;             WAIT_V(8); WAIT_L(0); BAR; MMA(1, 0, At, B0); MMA(1, 1, At, B1); BAR; SCHED;
.Lsp_1338:
	ds_read_b128 v[158:161], v156
	ds_read_b128 v[162:165], v156 offset:1024
	ds_read_b128 v[166:169], v156 offset:2048
	ds_read_b128 v[170:173], v156 offset:3072
	ds_read_b128 v[174:177], v156 offset:16384
	ds_read_b128 v[178:181], v156 offset:17408
	ds_read_b128 v[182:185], v156 offset:18432
	ds_read_b128 v[196:199], v156 offset:19456
	s_add_u32 s8, s75, s36
	s_addc_u32 s9, s81, s37
	s_add_u32 s8, s8, 0x62e6100
	s_addc_u32 s9, s9, 0
	s_add_u32 s31, s92, s36
	s_addc_u32 s95, s93, s37
	s_cmpk_eq_i32 s36, 0x700
	s_cselect_b32 s55, s50, s9
	s_cselect_b32 s54, s30, s8
	s_cselect_b32 s9, s74, s95
	s_cselect_b32 s8, s53, s31
	v_add_u32_e32 v194, 0xc000, v141
	v_lshl_add_u64 v[186:187], v[136:137], 0, s[36:37]
	v_readfirstlane_b32 s31, v194
	v_add_u32_e32 v194, 0xe000, v141
	s_mov_b32 m0, s31
	v_readfirstlane_b32 s31, v194
	ds_read_b128 v[200:203], v157
	ds_read_b128 v[212:215], v157 offset:1024
	ds_read_b128 v[216:219], v157 offset:2048
	ds_read_b128 v[220:223], v157 offset:3072
	ds_read_b128 v[224:227], v157 offset:4096
	ds_read_b128 v[228:231], v157 offset:5120
	ds_read_b128 v[232:235], v157 offset:6144
	ds_read_b128 v[236:239], v157 offset:7168
	global_load_lds_dwordx4 v[186:187], off
	v_lshl_add_u64 v[186:187], v[138:139], 0, s[36:37]
	s_mov_b32 m0, s31
	s_nop 0
	global_load_lds_dwordx4 v[186:187], off
	s_waitcnt vmcnt(8)
	s_waitcnt lgkmcnt(0)
	s_barrier
	v_mfma_f32_16x16x32_bf16 v[124:127], v[158:161], v[200:203], 0
	v_mfma_f32_16x16x32_bf16 v[120:123], v[166:169], v[200:203], 0
	v_mfma_f32_16x16x32_bf16 v[104:107], v[158:161], v[216:219], 0
	v_mfma_f32_16x16x32_bf16 v[108:111], v[166:169], v[216:219], 0
	v_mfma_f32_16x16x32_bf16 v[92:95], v[158:161], v[224:227], 0
	v_mfma_f32_16x16x32_bf16 v[88:91], v[166:169], v[224:227], 0
	v_mfma_f32_16x16x32_bf16 v[72:75], v[158:161], v[232:235], 0
	v_mfma_f32_16x16x32_bf16 v[76:79], v[166:169], v[232:235], 0
	v_mfma_f32_16x16x32_bf16 v[124:127], v[162:165], v[212:215], v[124:127]
	v_mfma_f32_16x16x32_bf16 v[120:123], v[170:173], v[212:215], v[120:123]
	v_mfma_f32_16x16x32_bf16 v[104:107], v[162:165], v[220:223], v[104:107]
	v_mfma_f32_16x16x32_bf16 v[108:111], v[170:173], v[220:223], v[108:111]
	v_mfma_f32_16x16x32_bf16 v[92:95], v[162:165], v[228:231], v[92:95]
	v_mfma_f32_16x16x32_bf16 v[88:91], v[170:173], v[228:231], v[88:91]
	v_mfma_f32_16x16x32_bf16 v[72:75], v[162:165], v[236:239], v[72:75]
	v_mfma_f32_16x16x32_bf16 v[76:79], v[170:173], v[236:239], v[76:79]
	v_mfma_f32_16x16x32_bf16 v[116:119], v[174:177], v[200:203], 0
	v_mfma_f32_16x16x32_bf16 v[112:115], v[182:185], v[200:203], 0
	v_mfma_f32_16x16x32_bf16 v[96:99], v[174:177], v[216:219], 0
	v_mfma_f32_16x16x32_bf16 v[100:103], v[182:185], v[216:219], 0
	v_mfma_f32_16x16x32_bf16 v[84:87], v[174:177], v[224:227], 0
	v_mfma_f32_16x16x32_bf16 v[80:83], v[182:185], v[224:227], 0
	v_mfma_f32_16x16x32_bf16 v[64:67], v[174:177], v[232:235], 0
	v_mfma_f32_16x16x32_bf16 v[68:71], v[182:185], v[232:235], 0
	v_mfma_f32_16x16x32_bf16 v[116:119], v[178:181], v[212:215], v[116:119]
	v_mfma_f32_16x16x32_bf16 v[112:115], v[196:199], v[212:215], v[112:115]
	v_mfma_f32_16x16x32_bf16 v[96:99], v[178:181], v[220:223], v[96:99]
	v_mfma_f32_16x16x32_bf16 v[100:103], v[196:199], v[220:223], v[100:103]
	v_mfma_f32_16x16x32_bf16 v[84:87], v[178:181], v[228:231], v[84:87]
	v_mfma_f32_16x16x32_bf16 v[80:83], v[196:199], v[228:231], v[80:83]
	v_mfma_f32_16x16x32_bf16 v[64:67], v[178:181], v[236:239], v[64:67]
	v_mfma_f32_16x16x32_bf16 v[68:71], v[196:199], v[236:239], v[68:71]
	s_barrier
	v_readfirstlane_b32 s31, v142
	v_lshl_add_u64 v[186:187], s[8:9], 0, v[128:129]
	s_mov_b32 m0, s31
	v_readfirstlane_b32 s31, v143
	s_add_u32 s96, s8, 0x40000
	ds_read_b128 v[200:203], v157 offset:16384
	ds_read_b128 v[212:215], v157 offset:17408
	ds_read_b128 v[216:219], v157 offset:18432
	ds_read_b128 v[220:223], v157 offset:19456
	ds_read_b128 v[224:227], v157 offset:20480
	ds_read_b128 v[228:231], v157 offset:21504
	ds_read_b128 v[232:235], v157 offset:22528
	ds_read_b128 v[236:239], v157 offset:23552
	global_load_lds_dwordx4 v[186:187], off
	v_lshl_add_u64 v[204:205], s[8:9], 0, v[130:131]
	s_mov_b32 m0, s31
	s_addc_u32 s97, s9, 0
	v_readfirstlane_b32 s31, v144
	global_load_lds_dwordx4 v[204:205], off
	v_lshl_add_u64 v[240:241], s[96:97], 0, v[128:129]
	s_mov_b32 m0, s31
	v_readfirstlane_b32 s31, v145
	global_load_lds_dwordx4 v[240:241], off
	v_lshl_add_u64 v[240:241], s[96:97], 0, v[130:131]
	s_mov_b32 m0, s31
	v_readfirstlane_b32 s31, v141
	global_load_lds_dwordx4 v[240:241], off
	v_lshl_add_u64 v[240:241], s[54:55], 0, v[128:129]
	s_mov_b32 m0, s31
	v_readfirstlane_b32 s31, v146
	global_load_lds_dwordx4 v[240:241], off
	v_lshl_add_u64 v[242:243], s[54:55], 0, v[130:131]
	s_mov_b32 m0, s31
	s_nop 0
	global_load_lds_dwordx4 v[242:243], off
	s_waitcnt vmcnt(8)
	s_waitcnt lgkmcnt(0)
	s_barrier
	v_mfma_f32_16x16x32_bf16 v[60:63], v[158:161], v[200:203], 0
	v_mfma_f32_16x16x32_bf16 v[56:59], v[166:169], v[200:203], 0
	v_mfma_f32_16x16x32_bf16 v[40:43], v[158:161], v[216:219], 0
	v_mfma_f32_16x16x32_bf16 v[44:47], v[166:169], v[216:219], 0
	v_mfma_f32_16x16x32_bf16 v[28:31], v[158:161], v[224:227], 0
	v_mfma_f32_16x16x32_bf16 v[24:27], v[166:169], v[224:227], 0
	v_mfma_f32_16x16x32_bf16 v[8:11], v[158:161], v[232:235], 0
	v_mfma_f32_16x16x32_bf16 v[12:15], v[166:169], v[232:235], 0
	v_mfma_f32_16x16x32_bf16 v[60:63], v[162:165], v[212:215], v[60:63]
	v_mfma_f32_16x16x32_bf16 v[56:59], v[170:173], v[212:215], v[56:59]
	v_mfma_f32_16x16x32_bf16 v[40:43], v[162:165], v[220:223], v[40:43]
	v_mfma_f32_16x16x32_bf16 v[44:47], v[170:173], v[220:223], v[44:47]
	v_mfma_f32_16x16x32_bf16 v[28:31], v[162:165], v[228:231], v[28:31]
	v_mfma_f32_16x16x32_bf16 v[24:27], v[170:173], v[228:231], v[24:27]
	v_mfma_f32_16x16x32_bf16 v[8:11], v[162:165], v[236:239], v[8:11]
	v_mfma_f32_16x16x32_bf16 v[12:15], v[170:173], v[236:239], v[12:15]
	v_mfma_f32_16x16x32_bf16 v[52:55], v[174:177], v[200:203], 0
	v_mfma_f32_16x16x32_bf16 v[48:51], v[182:185], v[200:203], 0
	v_mfma_f32_16x16x32_bf16 v[32:35], v[174:177], v[216:219], 0
	v_mfma_f32_16x16x32_bf16 v[36:39], v[182:185], v[216:219], 0
	v_mfma_f32_16x16x32_bf16 v[20:23], v[174:177], v[224:227], 0
	v_mfma_f32_16x16x32_bf16 v[16:19], v[182:185], v[224:227], 0
	v_mfma_f32_16x16x32_bf16 v[0:3], v[174:177], v[232:235], 0
	v_mfma_f32_16x16x32_bf16 v[4:7], v[182:185], v[232:235], 0
	v_mfma_f32_16x16x32_bf16 v[52:55], v[178:181], v[212:215], v[52:55]
	v_mfma_f32_16x16x32_bf16 v[48:51], v[196:199], v[212:215], v[48:51]
	v_mfma_f32_16x16x32_bf16 v[32:35], v[178:181], v[220:223], v[32:35]
	v_mfma_f32_16x16x32_bf16 v[36:39], v[196:199], v[220:223], v[36:39]
	v_mfma_f32_16x16x32_bf16 v[20:23], v[178:181], v[228:231], v[20:23]
	v_mfma_f32_16x16x32_bf16 v[16:19], v[196:199], v[228:231], v[16:19]
	v_mfma_f32_16x16x32_bf16 v[0:3], v[178:181], v[236:239], v[0:3]
	v_mfma_f32_16x16x32_bf16 v[4:7], v[196:199], v[236:239], v[4:7]
	s_barrier
	s_branch .Lkmid_1338
; #define WAIT_V(n) asm volatile("s_waitcnt vmcnt(" #n ")" ::: "memory")
; #define WAIT_L(n) asm volatile("s_waitcnt lgkmcnt(" #n ")" ::: "memory")
; #define BAR __builtin_amdgcn_s_barrier()
; #define SCHED __builtin_amdgcn_sched_barrier(0)
; #define STG_A(b, h, ptr) do { const char* _g = (ptr) + (h) * ahalf; LAS unsigned char* _l = lw + ((b) * 2 + (h)) * 16384; GLDS(_g + voa0, _l); GLDS(_g + voa1, _l + 8192); } while (0)
; #define STG_B(b, h, ptr) do { const char* _g = (ptr) + (h) * bhalf; LAS unsigned char* _l = lw + 65536 + ((b) * 2 + (h)) * 16384; GLDS(_g + vob0, _l); GLDS(_g + vob1, _l + 8192); } while (0)
; #define LDA(dst, b, h) _Pragma("unroll") for (int m = 0; m < 4; ++m) _Pragma("unroll") for (int k = 0; k < 2; ++k) dst[m][k] = *(const LAS bf16x8*)(la + ((b) * 2 + (h)) * 16384 + m * 2048 + k * 1024)
; #define LDB(dst, b, h) _Pragma("unroll") for (int n = 0; n < 2; ++n) _Pragma("unroll") for (int k = 0; k < 2; ++k) dst[n][k] = *(const LAS bf16x8*)(lb + ((b) * 2 + (h)) * 16384 + n * 2048 + k * 1024)
; #define MMA(ai, bj, Af, Bf) do { __builtin_amdgcn_s_setprio(1); \
;     _Pragma("unroll") for (int m = 0; m < 4; ++m) _Pragma("unroll") for (int n = 0; n < 2; ++n) _Pragma("unroll") for (int k = 0; k < 2; ++k) \
;         acc[ai][bj][m][n] = __builtin_amdgcn_mfma_f32_16x16x32_bf16(Bf[n][k], Af[m][k], acc[ai][bj][m][n], 0, 0, 0); \
;     __builtin_amdgcn_s_setprio(0); } while (0)
; template <int BMODE, class Epi, class TileFn>
; DEV void gemm_loop(LAS unsigned char* lds, const bf16_t* __restrict__ A, int lda, const bf16_t* __restrict__ B, int ldb, int K, const Epi& epi, int t0, int tstep, int tend, const TileFn& tf) {
;     ...
;         for (int t = 0; t < nt; t += 2) {
;             const bool last = (t == nt - 2);
;             const char* a1 = cA + (size_t)(t + 1) * 128;
;             const char* a2 = last ? nA : cA + (size_t)(t + 2) * 128;
;             const char* b2 = last ? nB : cB + (size_t)(t + 2) * bks;
;             const char* a3 = a2 + 128; const char* b3 = b2 + bks;
;             LDB(B0, 0, 0); LDB(B1, 0, 1); SCHED; LDA(At, 0, 0); STG_A(1, 1, a1);
;             WAIT_V(8); WAIT_L(0); BAR; MMA(0, 0, At, B0); MMA(0, 1, At, B1); BAR; SCHED;
;             LDA(At, 0, 1); STG_B(0, 0, b2); STG_B(0, 1, b2); STG_A(0, 0, a2);
;             WAIT_V(8); WAIT_L(0); BAR; MMA(1, 0, At, B0); MMA(1, 1, At, B1); BAR; SCHED;
.LBB0_1338:
	ds_read_b128 v[158:161], v156
	ds_read_b128 v[162:165], v156 offset:1024
	ds_read_b128 v[166:169], v156 offset:2048
	ds_read_b128 v[170:173], v156 offset:3072
	ds_read_b128 v[174:177], v156 offset:16384
	ds_read_b128 v[178:181], v156 offset:17408
	ds_read_b128 v[182:185], v156 offset:18432
	ds_read_b128 v[196:199], v156 offset:19456
	s_add_u32 s8, s75, s36
	s_addc_u32 s9, s81, s37
	s_add_u32 s8, s8, 0x62e6100
	s_addc_u32 s9, s9, 0
	s_add_u32 s31, s92, s36
	s_addc_u32 s95, s93, s37
	s_cmpk_eq_i32 s36, 0x700
	s_cselect_b32 s55, s50, s9
	s_cselect_b32 s54, s30, s8
	s_cselect_b32 s9, s74, s95
	s_cselect_b32 s8, s53, s31
	v_add_u32_e32 v194, 0xc000, v141
	v_lshl_add_u64 v[186:187], v[136:137], 0, s[36:37]
	v_readfirstlane_b32 s31, v194
	v_add_u32_e32 v194, 0xe000, v141
	s_mov_b32 m0, s31
	v_readfirstlane_b32 s31, v194
	ds_read_b128 v[200:203], v157
	ds_read_b128 v[212:215], v157 offset:1024
	ds_read_b128 v[216:219], v157 offset:2048
	ds_read_b128 v[220:223], v157 offset:3072
	ds_read_b128 v[224:227], v157 offset:4096
	ds_read_b128 v[228:231], v157 offset:5120
	ds_read_b128 v[232:235], v157 offset:6144
	ds_read_b128 v[236:239], v157 offset:7168
	global_load_lds_dwordx4 v[186:187], off
	v_lshl_add_u64 v[186:187], v[138:139], 0, s[36:37]
	s_mov_b32 m0, s31
	s_nop 0
	global_load_lds_dwordx4 v[186:187], off
	s_waitcnt vmcnt(8)
	s_waitcnt lgkmcnt(0)
	s_barrier
	v_mfma_f32_16x16x32_bf16 v[124:127], v[158:161], v[200:203], v[124:127]
	v_mfma_f32_16x16x32_bf16 v[120:123], v[166:169], v[200:203], v[120:123]
	v_mfma_f32_16x16x32_bf16 v[104:107], v[158:161], v[216:219], v[104:107]
	v_mfma_f32_16x16x32_bf16 v[108:111], v[166:169], v[216:219], v[108:111]
	v_mfma_f32_16x16x32_bf16 v[92:95], v[158:161], v[224:227], v[92:95]
	v_mfma_f32_16x16x32_bf16 v[88:91], v[166:169], v[224:227], v[88:91]
	v_mfma_f32_16x16x32_bf16 v[72:75], v[158:161], v[232:235], v[72:75]
	v_mfma_f32_16x16x32_bf16 v[76:79], v[166:169], v[232:235], v[76:79]
	v_mfma_f32_16x16x32_bf16 v[124:127], v[162:165], v[212:215], v[124:127]
	v_mfma_f32_16x16x32_bf16 v[120:123], v[170:173], v[212:215], v[120:123]
	v_mfma_f32_16x16x32_bf16 v[104:107], v[162:165], v[220:223], v[104:107]
	v_mfma_f32_16x16x32_bf16 v[108:111], v[170:173], v[220:223], v[108:111]
	v_mfma_f32_16x16x32_bf16 v[92:95], v[162:165], v[228:231], v[92:95]
	v_mfma_f32_16x16x32_bf16 v[88:91], v[170:173], v[228:231], v[88:91]
	v_mfma_f32_16x16x32_bf16 v[72:75], v[162:165], v[236:239], v[72:75]
	v_mfma_f32_16x16x32_bf16 v[76:79], v[170:173], v[236:239], v[76:79]
	v_mfma_f32_16x16x32_bf16 v[116:119], v[174:177], v[200:203], v[116:119]
	v_mfma_f32_16x16x32_bf16 v[112:115], v[182:185], v[200:203], v[112:115]
	v_mfma_f32_16x16x32_bf16 v[96:99], v[174:177], v[216:219], v[96:99]
	v_mfma_f32_16x16x32_bf16 v[100:103], v[182:185], v[216:219], v[100:103]
	v_mfma_f32_16x16x32_bf16 v[84:87], v[174:177], v[224:227], v[84:87]
	v_mfma_f32_16x16x32_bf16 v[80:83], v[182:185], v[224:227], v[80:83]
	v_mfma_f32_16x16x32_bf16 v[64:67], v[174:177], v[232:235], v[64:67]
	v_mfma_f32_16x16x32_bf16 v[68:71], v[182:185], v[232:235], v[68:71]
	v_mfma_f32_16x16x32_bf16 v[116:119], v[178:181], v[212:215], v[116:119]
	v_mfma_f32_16x16x32_bf16 v[112:115], v[196:199], v[212:215], v[112:115]
	v_mfma_f32_16x16x32_bf16 v[96:99], v[178:181], v[220:223], v[96:99]
	v_mfma_f32_16x16x32_bf16 v[100:103], v[196:199], v[220:223], v[100:103]
	v_mfma_f32_16x16x32_bf16 v[84:87], v[178:181], v[228:231], v[84:87]
	v_mfma_f32_16x16x32_bf16 v[80:83], v[196:199], v[228:231], v[80:83]
	v_mfma_f32_16x16x32_bf16 v[64:67], v[178:181], v[236:239], v[64:67]
	v_mfma_f32_16x16x32_bf16 v[68:71], v[196:199], v[236:239], v[68:71]
	s_barrier
	v_readfirstlane_b32 s31, v142
	v_lshl_add_u64 v[186:187], s[8:9], 0, v[128:129]
	s_mov_b32 m0, s31
	v_readfirstlane_b32 s31, v143
	s_add_u32 s96, s8, 0x40000
	ds_read_b128 v[200:203], v157 offset:16384
	ds_read_b128 v[212:215], v157 offset:17408
	ds_read_b128 v[216:219], v157 offset:18432
	ds_read_b128 v[220:223], v157 offset:19456
	ds_read_b128 v[224:227], v157 offset:20480
	ds_read_b128 v[228:231], v157 offset:21504
	ds_read_b128 v[232:235], v157 offset:22528
	ds_read_b128 v[236:239], v157 offset:23552
	global_load_lds_dwordx4 v[186:187], off
	v_lshl_add_u64 v[204:205], s[8:9], 0, v[130:131]
	s_mov_b32 m0, s31
	s_addc_u32 s97, s9, 0
	v_readfirstlane_b32 s31, v144
	global_load_lds_dwordx4 v[204:205], off
	v_lshl_add_u64 v[240:241], s[96:97], 0, v[128:129]
	s_mov_b32 m0, s31
	v_readfirstlane_b32 s31, v145
	global_load_lds_dwordx4 v[240:241], off
	v_lshl_add_u64 v[240:241], s[96:97], 0, v[130:131]
	s_mov_b32 m0, s31
	v_readfirstlane_b32 s31, v141
	global_load_lds_dwordx4 v[240:241], off
	v_lshl_add_u64 v[240:241], s[54:55], 0, v[128:129]
	s_mov_b32 m0, s31
	v_readfirstlane_b32 s31, v146
	global_load_lds_dwordx4 v[240:241], off
	v_lshl_add_u64 v[242:243], s[54:55], 0, v[130:131]
	s_mov_b32 m0, s31
	s_nop 0
	global_load_lds_dwordx4 v[242:243], off
	s_waitcnt vmcnt(8)
	s_waitcnt lgkmcnt(0)
	s_barrier
; #define WAIT_V(n) asm volatile("s_waitcnt vmcnt(" #n ")" ::: "memory")
; #define WAIT_L(n) asm volatile("s_waitcnt lgkmcnt(" #n ")" ::: "memory")
; #define BAR __builtin_amdgcn_s_barrier()
; #define SCHED __builtin_amdgcn_sched_barrier(0)
; #define STG_A(b, h, ptr) do { const char* _g = (ptr) + (h) * ahalf; LAS unsigned char* _l = lw + ((b) * 2 + (h)) * 16384; GLDS(_g + voa0, _l); GLDS(_g + voa1, _l + 8192); } while (0)
; #define LDA(dst, b, h) _Pragma("unroll") for (int m = 0; m < 4; ++m) _Pragma("unroll") for (int k = 0; k < 2; ++k) dst[m][k] = *(const LAS bf16x8*)(la + ((b) * 2 + (h)) * 16384 + m * 2048 + k * 1024)
; #define LDB(dst, b, h) _Pragma("unroll") for (int n = 0; n < 2; ++n) _Pragma("unroll") for (int k = 0; k < 2; ++k) dst[n][k] = *(const LAS bf16x8*)(lb + ((b) * 2 + (h)) * 16384 + n * 2048 + k * 1024)
; #define MMA(ai, bj, Af, Bf) do { __builtin_amdgcn_s_setprio(1); \
;     _Pragma("unroll") for (int m = 0; m < 4; ++m) _Pragma("unroll") for (int n = 0; n < 2; ++n) _Pragma("unroll") for (int k = 0; k < 2; ++k) \
;         acc[ai][bj][m][n] = __builtin_amdgcn_mfma_f32_16x16x32_bf16(Bf[n][k], Af[m][k], acc[ai][bj][m][n], 0, 0, 0); \
;     __builtin_amdgcn_s_setprio(0); } while (0)
; template <int BMODE, class Epi, class TileFn>
; DEV void gemm_loop(LAS unsigned char* lds, const bf16_t* __restrict__ A, int lda, const bf16_t* __restrict__ B, int ldb, int K, const Epi& epi, int t0, int tstep, int tend, const TileFn& tf) {
;     ...
;             WAIT_V(8); WAIT_L(0); BAR; MMA(1, 0, At, B0); MMA(1, 1, At, B1); BAR; SCHED;
;             LDB(B0, 1, 0); LDB(B1, 1, 1); SCHED; LDA(At, 1, 0); STG_A(0, 1, a2);
;             WAIT_V(8); WAIT_L(0); BAR; MMA(0, 0, At, B0); MMA(0, 1, At, B1); BAR; SCHED;
	v_mfma_f32_16x16x32_bf16 v[60:63], v[158:161], v[200:203], v[60:63]
	v_mfma_f32_16x16x32_bf16 v[56:59], v[166:169], v[200:203], v[56:59]
	v_mfma_f32_16x16x32_bf16 v[40:43], v[158:161], v[216:219], v[40:43]
	v_mfma_f32_16x16x32_bf16 v[44:47], v[166:169], v[216:219], v[44:47]
	v_mfma_f32_16x16x32_bf16 v[28:31], v[158:161], v[224:227], v[28:31]
	v_mfma_f32_16x16x32_bf16 v[24:27], v[166:169], v[224:227], v[24:27]
	v_mfma_f32_16x16x32_bf16 v[8:11], v[158:161], v[232:235], v[8:11]
	v_mfma_f32_16x16x32_bf16 v[12:15], v[166:169], v[232:235], v[12:15]
	v_mfma_f32_16x16x32_bf16 v[60:63], v[162:165], v[212:215], v[60:63]
	v_mfma_f32_16x16x32_bf16 v[56:59], v[170:173], v[212:215], v[56:59]
	v_mfma_f32_16x16x32_bf16 v[40:43], v[162:165], v[220:223], v[40:43]
	v_mfma_f32_16x16x32_bf16 v[44:47], v[170:173], v[220:223], v[44:47]
	v_mfma_f32_16x16x32_bf16 v[28:31], v[162:165], v[228:231], v[28:31]
	v_mfma_f32_16x16x32_bf16 v[24:27], v[170:173], v[228:231], v[24:27]
	v_mfma_f32_16x16x32_bf16 v[8:11], v[162:165], v[236:239], v[8:11]
	v_mfma_f32_16x16x32_bf16 v[12:15], v[170:173], v[236:239], v[12:15]
	v_mfma_f32_16x16x32_bf16 v[52:55], v[174:177], v[200:203], v[52:55]
	v_mfma_f32_16x16x32_bf16 v[48:51], v[182:185], v[200:203], v[48:51]
	v_mfma_f32_16x16x32_bf16 v[32:35], v[174:177], v[216:219], v[32:35]
	v_mfma_f32_16x16x32_bf16 v[36:39], v[182:185], v[216:219], v[36:39]
	v_mfma_f32_16x16x32_bf16 v[20:23], v[174:177], v[224:227], v[20:23]
	v_mfma_f32_16x16x32_bf16 v[16:19], v[182:185], v[224:227], v[16:19]
	v_mfma_f32_16x16x32_bf16 v[0:3], v[174:177], v[232:235], v[0:3]
	v_mfma_f32_16x16x32_bf16 v[4:7], v[182:185], v[232:235], v[4:7]
	v_mfma_f32_16x16x32_bf16 v[52:55], v[178:181], v[212:215], v[52:55]
	v_mfma_f32_16x16x32_bf16 v[48:51], v[196:199], v[212:215], v[48:51]
	v_mfma_f32_16x16x32_bf16 v[32:35], v[178:181], v[220:223], v[32:35]
	v_mfma_f32_16x16x32_bf16 v[36:39], v[196:199], v[220:223], v[36:39]
	v_mfma_f32_16x16x32_bf16 v[20:23], v[178:181], v[228:231], v[20:23]
	v_mfma_f32_16x16x32_bf16 v[16:19], v[196:199], v[228:231], v[16:19]
	v_mfma_f32_16x16x32_bf16 v[0:3], v[178:181], v[236:239], v[0:3]
	v_mfma_f32_16x16x32_bf16 v[4:7], v[196:199], v[236:239], v[4:7]
	s_barrier
.Lkmid_1338:
	ds_read_b128 v[158:161], v156 offset:32768
	ds_read_b128 v[162:165], v156 offset:33792
	ds_read_b128 v[166:169], v156 offset:34816
	ds_read_b128 v[170:173], v156 offset:35840
	ds_read_b128 v[174:177], v156 offset:49152
	ds_read_b128 v[178:181], v156 offset:50176
	ds_read_b128 v[182:185], v156 offset:51200
	ds_read_b128 v[196:199], v156 offset:52224
	s_add_u32 s54, s54, 0x40000
	s_addc_u32 s55, s55, 0
	v_readfirstlane_b32 s31, v147
	v_lshl_add_u64 v[244:245], s[54:55], 0, v[128:129]
	s_mov_b32 m0, s31
	v_readfirstlane_b32 s31, v148
	ds_read_b128 v[200:203], v157 offset:32768
	ds_read_b128 v[212:215], v157 offset:33792
	ds_read_b128 v[216:219], v157 offset:34816
	ds_read_b128 v[220:223], v157 offset:35840
	ds_read_b128 v[224:227], v157 offset:36864
	ds_read_b128 v[228:231], v157 offset:37888
	ds_read_b128 v[232:235], v157 offset:38912
	ds_read_b128 v[236:239], v157 offset:39936
	global_load_lds_dwordx4 v[244:245], off
	v_lshl_add_u64 v[244:245], s[54:55], 0, v[130:131]
	s_mov_b32 m0, s31
	s_nop 0
	global_load_lds_dwordx4 v[244:245], off
	s_waitcnt vmcnt(8)
	s_waitcnt lgkmcnt(0)
	s_barrier
	v_mfma_f32_16x16x32_bf16 v[124:127], v[158:161], v[200:203], v[124:127]
	v_mfma_f32_16x16x32_bf16 v[120:123], v[166:169], v[200:203], v[120:123]
	v_mfma_f32_16x16x32_bf16 v[104:107], v[158:161], v[216:219], v[104:107]
	v_mfma_f32_16x16x32_bf16 v[108:111], v[166:169], v[216:219], v[108:111]
	v_mfma_f32_16x16x32_bf16 v[92:95], v[158:161], v[224:227], v[92:95]
	v_mfma_f32_16x16x32_bf16 v[88:91], v[166:169], v[224:227], v[88:91]
	v_mfma_f32_16x16x32_bf16 v[72:75], v[158:161], v[232:235], v[72:75]
	v_mfma_f32_16x16x32_bf16 v[76:79], v[166:169], v[232:235], v[76:79]
	v_mfma_f32_16x16x32_bf16 v[124:127], v[162:165], v[212:215], v[124:127]
	v_mfma_f32_16x16x32_bf16 v[120:123], v[170:173], v[212:215], v[120:123]
	v_mfma_f32_16x16x32_bf16 v[104:107], v[162:165], v[220:223], v[104:107]
	v_mfma_f32_16x16x32_bf16 v[108:111], v[170:173], v[220:223], v[108:111]
	v_mfma_f32_16x16x32_bf16 v[92:95], v[162:165], v[228:231], v[92:95]
	v_mfma_f32_16x16x32_bf16 v[88:91], v[170:173], v[228:231], v[88:91]
	v_mfma_f32_16x16x32_bf16 v[72:75], v[162:165], v[236:239], v[72:75]
	v_mfma_f32_16x16x32_bf16 v[76:79], v[170:173], v[236:239], v[76:79]
	v_mfma_f32_16x16x32_bf16 v[116:119], v[174:177], v[200:203], v[116:119]
	v_mfma_f32_16x16x32_bf16 v[112:115], v[182:185], v[200:203], v[112:115]
	v_mfma_f32_16x16x32_bf16 v[96:99], v[174:177], v[216:219], v[96:99]
	v_mfma_f32_16x16x32_bf16 v[100:103], v[182:185], v[216:219], v[100:103]
	v_mfma_f32_16x16x32_bf16 v[84:87], v[174:177], v[224:227], v[84:87]
	v_mfma_f32_16x16x32_bf16 v[80:83], v[182:185], v[224:227], v[80:83]
	v_mfma_f32_16x16x32_bf16 v[64:67], v[174:177], v[232:235], v[64:67]
	v_mfma_f32_16x16x32_bf16 v[68:71], v[182:185], v[232:235], v[68:71]
	v_mfma_f32_16x16x32_bf16 v[116:119], v[178:181], v[212:215], v[116:119]
	v_mfma_f32_16x16x32_bf16 v[112:115], v[196:199], v[212:215], v[112:115]
	v_mfma_f32_16x16x32_bf16 v[96:99], v[178:181], v[220:223], v[96:99]
	v_mfma_f32_16x16x32_bf16 v[100:103], v[196:199], v[220:223], v[100:103]
	v_mfma_f32_16x16x32_bf16 v[84:87], v[178:181], v[228:231], v[84:87]
	v_mfma_f32_16x16x32_bf16 v[80:83], v[196:199], v[228:231], v[80:83]
	v_mfma_f32_16x16x32_bf16 v[64:67], v[178:181], v[236:239], v[64:67]
	v_mfma_f32_16x16x32_bf16 v[68:71], v[196:199], v[236:239], v[68:71]
	s_barrier
; #define WAIT_V(n) asm volatile("s_waitcnt vmcnt(" #n ")" ::: "memory")
; #define WAIT_L(n) asm volatile("s_waitcnt lgkmcnt(" #n ")" ::: "memory")
; #define BAR __builtin_amdgcn_s_barrier()
; #define SCHED __builtin_amdgcn_sched_barrier(0)
; #define STG_A(b, h, ptr) do { const char* _g = (ptr) + (h) * ahalf; LAS unsigned char* _l = lw + ((b) * 2 + (h)) * 16384; GLDS(_g + voa0, _l); GLDS(_g + voa1, _l + 8192); } while (0)
; #define STG_B(b, h, ptr) do { const char* _g = (ptr) + (h) * bhalf; LAS unsigned char* _l = lw + 65536 + ((b) * 2 + (h)) * 16384; GLDS(_g + vob0, _l); GLDS(_g + vob1, _l + 8192); } while (0)
; #define LDA(dst, b, h) _Pragma("unroll") for (int m = 0; m < 4; ++m) _Pragma("unroll") for (int k = 0; k < 2; ++k) dst[m][k] = *(const LAS bf16x8*)(la + ((b) * 2 + (h)) * 16384 + m * 2048 + k * 1024)
; #define MMA(ai, bj, Af, Bf) do { __builtin_amdgcn_s_setprio(1); \
;     _Pragma("unroll") for (int m = 0; m < 4; ++m) _Pragma("unroll") for (int n = 0; n < 2; ++n) _Pragma("unroll") for (int k = 0; k < 2; ++k) \
;         acc[ai][bj][m][n] = __builtin_amdgcn_mfma_f32_16x16x32_bf16(Bf[n][k], Af[m][k], acc[ai][bj][m][n], 0, 0, 0); \
;     __builtin_amdgcn_s_setprio(0); } while (0)
; template <int BMODE, class Epi, class TileFn>
; DEV void gemm_loop(LAS unsigned char* lds, const bf16_t* __restrict__ A, int lda, const bf16_t* __restrict__ B, int ldb, int K, const Epi& epi, int t0, int tstep, int tend, const TileFn& tf) {
;     ...
;             LDA(At, 1, 1); STG_B(1, 0, b3); STG_B(1, 1, b3); STG_A(1, 0, a3);
;             WAIT_V(8); WAIT_L(0); BAR; MMA(1, 0, At, B0); MMA(1, 1, At, B1); BAR; SCHED;
;         }
;         if (wr == 0) BAR;
	v_readfirstlane_b32 s31, v149
	v_lshl_add_u64 v[186:187], v[186:187], 0, s[2:3]
	s_mov_b32 m0, s31
	v_readfirstlane_b32 s31, v150
	s_add_u32 s8, s8, 0x40080
	ds_read_b128 v[200:203], v157 offset:49152
	ds_read_b128 v[212:215], v157 offset:50176
	ds_read_b128 v[216:219], v157 offset:51200
	ds_read_b128 v[220:223], v157 offset:52224
	ds_read_b128 v[224:227], v157 offset:53248
	ds_read_b128 v[228:231], v157 offset:54272
	ds_read_b128 v[232:235], v157 offset:55296
	ds_read_b128 v[236:239], v157 offset:56320
	global_load_lds_dwordx4 v[186:187], off
	v_lshl_add_u64 v[186:187], v[204:205], 0, s[2:3]
	s_mov_b32 m0, s31
	s_addc_u32 s9, s9, 0
	v_readfirstlane_b32 s31, v153
	global_load_lds_dwordx4 v[186:187], off
	v_lshl_add_u64 v[186:187], s[8:9], 0, v[128:129]
	s_mov_b32 m0, s31
	s_nop 0
	global_load_lds_dwordx4 v[186:187], off
	v_lshl_add_u64 v[186:187], s[8:9], 0, v[130:131]
	v_readfirstlane_b32 s8, v154
	s_mov_b32 m0, s8
	v_readfirstlane_b32 s8, v151
	global_load_lds_dwordx4 v[186:187], off
	v_lshl_add_u64 v[186:187], v[240:241], 0, s[2:3]
	s_mov_b32 m0, s8
	v_readfirstlane_b32 s8, v152
	global_load_lds_dwordx4 v[186:187], off
	v_lshl_add_u64 v[186:187], v[242:243], 0, s[2:3]
	s_mov_b32 m0, s8
	s_nop 0
	global_load_lds_dwordx4 v[186:187], off
	s_waitcnt vmcnt(8)
	s_waitcnt lgkmcnt(0)
	s_barrier
	v_mfma_f32_16x16x32_bf16 v[60:63], v[158:161], v[200:203], v[60:63]
	v_mfma_f32_16x16x32_bf16 v[56:59], v[166:169], v[200:203], v[56:59]
	v_mfma_f32_16x16x32_bf16 v[40:43], v[158:161], v[216:219], v[40:43]
	v_mfma_f32_16x16x32_bf16 v[44:47], v[166:169], v[216:219], v[44:47]
	v_mfma_f32_16x16x32_bf16 v[28:31], v[158:161], v[224:227], v[28:31]
	v_mfma_f32_16x16x32_bf16 v[24:27], v[166:169], v[224:227], v[24:27]
	v_mfma_f32_16x16x32_bf16 v[8:11], v[158:161], v[232:235], v[8:11]
	v_mfma_f32_16x16x32_bf16 v[12:15], v[166:169], v[232:235], v[12:15]
	v_mfma_f32_16x16x32_bf16 v[60:63], v[162:165], v[212:215], v[60:63]
	v_mfma_f32_16x16x32_bf16 v[56:59], v[170:173], v[212:215], v[56:59]
	v_mfma_f32_16x16x32_bf16 v[40:43], v[162:165], v[220:223], v[40:43]
	v_mfma_f32_16x16x32_bf16 v[44:47], v[170:173], v[220:223], v[44:47]
	v_mfma_f32_16x16x32_bf16 v[28:31], v[162:165], v[228:231], v[28:31]
	v_mfma_f32_16x16x32_bf16 v[24:27], v[170:173], v[228:231], v[24:27]
	v_mfma_f32_16x16x32_bf16 v[8:11], v[162:165], v[236:239], v[8:11]
	v_mfma_f32_16x16x32_bf16 v[12:15], v[170:173], v[236:239], v[12:15]
	v_mfma_f32_16x16x32_bf16 v[52:55], v[174:177], v[200:203], v[52:55]
	v_mfma_f32_16x16x32_bf16 v[48:51], v[182:185], v[200:203], v[48:51]
	v_mfma_f32_16x16x32_bf16 v[32:35], v[174:177], v[216:219], v[32:35]
	v_mfma_f32_16x16x32_bf16 v[36:39], v[182:185], v[216:219], v[36:39]
	v_mfma_f32_16x16x32_bf16 v[20:23], v[174:177], v[224:227], v[20:23]
	v_mfma_f32_16x16x32_bf16 v[16:19], v[182:185], v[224:227], v[16:19]
	v_mfma_f32_16x16x32_bf16 v[0:3], v[174:177], v[232:235], v[0:3]
	v_mfma_f32_16x16x32_bf16 v[4:7], v[182:185], v[232:235], v[4:7]
	v_mfma_f32_16x16x32_bf16 v[52:55], v[178:181], v[212:215], v[52:55]
	v_mfma_f32_16x16x32_bf16 v[48:51], v[196:199], v[212:215], v[48:51]
	v_mfma_f32_16x16x32_bf16 v[32:35], v[178:181], v[220:223], v[32:35]
	v_mfma_f32_16x16x32_bf16 v[36:39], v[196:199], v[220:223], v[36:39]
	v_mfma_f32_16x16x32_bf16 v[20:23], v[178:181], v[228:231], v[20:23]
	v_mfma_f32_16x16x32_bf16 v[16:19], v[196:199], v[228:231], v[16:19]
	v_mfma_f32_16x16x32_bf16 v[0:3], v[178:181], v[236:239], v[0:3]
	v_mfma_f32_16x16x32_bf16 v[4:7], v[196:199], v[236:239], v[4:7]
	s_barrier
	s_add_i32 s94, s94, 2
	s_add_u32 s36, s36, 0x100
	s_addc_u32 s37, s37, 0
	s_cmp_gt_u32 s94, 13
	s_cbranch_scc0 .LBB0_1338
	s_setprio 0
	s_and_saveexec_b64 s[8:9], s[44:45]
	s_cbranch_execz .LBB0_1341
	s_barrier

; #define WAIT_V(n) asm volatile("s_waitcnt vmcnt(" #n ")" ::: "memory")
; #define WAIT_L(n) asm volatile("s_waitcnt lgkmcnt(" #n ")" ::: "memory")
; #define BAR __builtin_amdgcn_s_barrier()
; #define SCHED __builtin_amdgcn_sched_barrier(0)
; #define STG_A(b, h, ptr) do { const char* _g = (ptr) + (h) * ahalf; LAS unsigned char* _l = lw + ((b) * 2 + (h)) * 16384; GLDS(_g + voa0, _l); GLDS(_g + voa1, _l + 8192); } while (0)
; #define STG_B(b, h, ptr) do { const char* _g = (ptr) + (h) * bhalf; LAS unsigned char* _l = lw + 65536 + ((b) * 2 + (h)) * 16384; GLDS(_g + vob0, _l); GLDS(_g + vob1, _l + 8192); } while (0)
; #define LDA(dst, b, h) _Pragma("unroll") for (int m = 0; m < 4; ++m) _Pragma("unroll") for (int k = 0; k < 2; ++k) dst[m][k] = *(const LAS bf16x8*)(la + ((b) * 2 + (h)) * 16384 + m * 2048 + k * 1024)
; #define LDB(dst, b, h) _Pragma("unroll") for (int n = 0; n < 2; ++n) _Pragma("unroll") for (int k = 0; k < 2; ++k) dst[n][k] = *(const LAS bf16x8*)(lb + ((b) * 2 + (h)) * 16384 + n * 2048 + k * 1024)
; #define MMA(ai, bj, Af, Bf) do { __builtin_amdgcn_s_setprio(1); \
;     _Pragma("unroll") for (int m = 0; m < 4; ++m) _Pragma("unroll") for (int n = 0; n < 2; ++n) _Pragma("unroll") for (int k = 0; k < 2; ++k) \
;         acc[ai][bj][m][n] = __builtin_amdgcn_mfma_f32_16x16x32_bf16(Bf[n][k], Af[m][k], acc[ai][bj][m][n], 0, 0, 0); \
;     __builtin_amdgcn_s_setprio(0); } while (0)
; template <int BMODE, class Epi, class TileFn>
; DEV void gemm_loop(LAS unsigned char* lds, const bf16_t* __restrict__ A, int lda, const bf16_t* __restrict__ B, int ldb, int K, const Epi& epi, int t0, int tstep, int tend, const TileFn& tf) {
;     ...
;         for (int t = 0; t < nt; t += 2) {
;             const bool last = (t == nt - 2);
;             const char* a1 = cA + (size_t)(t + 1) * 128;
;             const char* a2 = last ? nA : cA + (size_t)(t + 2) * 128;
;             const char* b2 = last ? nB : cB + (size_t)(t + 2) * bks;
;             const char* a3 = a2 + 128; const char* b3 = b2 + bks;
;             LDB(B0, 0, 0); LDB(B1, 0, 1); SCHED; LDA(At, 0, 0); STG_A(1, 1, a1);
;             WAIT_V(8); WAIT_L(0); BAR; MMA(0, 0, At, B0); MMA(0, 1, At, B1); BAR; SCHED;
;             LDA(At, 0, 1); STG_B(0, 0, b2); STG_B(0, 1, b2); STG_A(0, 0, a2);
;             WAIT_V(8); WAIT_L(0); BAR; MMA(1, 0, At, B0); MMA(1, 1, At, B1); BAR; SCHED;
.Lsp_1441:
	ds_read_b128 v[132:135], v225
	ds_read_b128 v[136:139], v225 offset:1024
	ds_read_b128 v[140:143], v225 offset:2048
	ds_read_b128 v[144:147], v225 offset:3072
	ds_read_b128 v[148:151], v225 offset:16384
	ds_read_b128 v[152:155], v225 offset:17408
	ds_read_b128 v[156:159], v225 offset:18432
	ds_read_b128 v[160:163], v225 offset:19456
	s_add_u32 s8, s55, s0
	s_addc_u32 s9, s74, s1
	s_add_u32 s8, s8, 0xc366100
	s_addc_u32 s9, s9, 0
	s_add_u32 s31, s75, s0
	s_addc_u32 s80, s76, s1
	s_cmpk_eq_i32 s0, 0x1500
	s_cselect_b32 s53, s37, s9
	s_cselect_b32 s52, s30, s8
	s_cselect_b32 s9, s54, s80
	s_cselect_b32 s8, s50, s31
	v_add_u32_e32 v194, 0xc000, v211
	v_lshl_add_u64 v[204:205], v[120:121], 0, s[0:1]
	v_readfirstlane_b32 s31, v194
	v_add_u32_e32 v194, 0xe000, v211
	s_mov_b32 m0, s31
	v_readfirstlane_b32 s31, v194
	ds_read_b128 v[164:167], v226
	ds_read_b128 v[168:171], v226 offset:1024
	ds_read_b128 v[172:175], v226 offset:2048
	ds_read_b128 v[176:179], v226 offset:3072
	ds_read_b128 v[180:183], v226 offset:4096
	ds_read_b128 v[228:231], v226 offset:5120
	ds_read_b128 v[232:235], v226 offset:6144
	ds_read_b128 v[236:239], v226 offset:7168
	global_load_lds_dwordx4 v[204:205], off
	v_lshl_add_u64 v[204:205], v[122:123], 0, s[0:1]
	s_mov_b32 m0, s31
	s_nop 0
	global_load_lds_dwordx4 v[204:205], off
	s_waitcnt vmcnt(8)
	s_waitcnt lgkmcnt(0)
	s_barrier
	v_mfma_f32_16x16x32_bf16 v[128:131], v[132:135], v[164:167], 0
	v_mfma_f32_16x16x32_bf16 v[124:127], v[140:143], v[164:167], 0
	v_mfma_f32_16x16x32_bf16 v[108:111], v[132:135], v[172:175], 0
	v_mfma_f32_16x16x32_bf16 v[104:107], v[140:143], v[172:175], 0
	v_mfma_f32_16x16x32_bf16 v[92:95], v[132:135], v[180:183], 0
	v_mfma_f32_16x16x32_bf16 v[88:91], v[140:143], v[180:183], 0
	v_mfma_f32_16x16x32_bf16 v[76:79], v[132:135], v[232:235], 0
	v_mfma_f32_16x16x32_bf16 v[72:75], v[140:143], v[232:235], 0
	v_mfma_f32_16x16x32_bf16 v[128:131], v[136:139], v[168:171], v[128:131]
	v_mfma_f32_16x16x32_bf16 v[124:127], v[144:147], v[168:171], v[124:127]
	v_mfma_f32_16x16x32_bf16 v[108:111], v[136:139], v[176:179], v[108:111]
	v_mfma_f32_16x16x32_bf16 v[104:107], v[144:147], v[176:179], v[104:107]
	v_mfma_f32_16x16x32_bf16 v[92:95], v[136:139], v[228:231], v[92:95]
	v_mfma_f32_16x16x32_bf16 v[88:91], v[144:147], v[228:231], v[88:91]
	v_mfma_f32_16x16x32_bf16 v[76:79], v[136:139], v[236:239], v[76:79]
	v_mfma_f32_16x16x32_bf16 v[72:75], v[144:147], v[236:239], v[72:75]
	v_mfma_f32_16x16x32_bf16 v[116:119], v[148:151], v[164:167], 0
	v_mfma_f32_16x16x32_bf16 v[112:115], v[156:159], v[164:167], 0
	v_mfma_f32_16x16x32_bf16 v[100:103], v[148:151], v[172:175], 0
	v_mfma_f32_16x16x32_bf16 v[96:99], v[156:159], v[172:175], 0
	v_mfma_f32_16x16x32_bf16 v[84:87], v[148:151], v[180:183], 0
	v_mfma_f32_16x16x32_bf16 v[80:83], v[156:159], v[180:183], 0
	v_mfma_f32_16x16x32_bf16 v[68:71], v[148:151], v[232:235], 0
	v_mfma_f32_16x16x32_bf16 v[64:67], v[156:159], v[232:235], 0
	v_mfma_f32_16x16x32_bf16 v[116:119], v[152:155], v[168:171], v[116:119]
	v_mfma_f32_16x16x32_bf16 v[112:115], v[160:163], v[168:171], v[112:115]
	v_mfma_f32_16x16x32_bf16 v[100:103], v[152:155], v[176:179], v[100:103]
	v_mfma_f32_16x16x32_bf16 v[96:99], v[160:163], v[176:179], v[96:99]
	v_mfma_f32_16x16x32_bf16 v[84:87], v[152:155], v[228:231], v[84:87]
	v_mfma_f32_16x16x32_bf16 v[80:83], v[160:163], v[228:231], v[80:83]
	v_mfma_f32_16x16x32_bf16 v[68:71], v[152:155], v[236:239], v[68:71]
	v_mfma_f32_16x16x32_bf16 v[64:67], v[160:163], v[236:239], v[64:67]
	s_barrier
	v_readfirstlane_b32 s31, v212
	v_lshl_add_u64 v[204:205], s[8:9], 0, v[196:197]
	s_mov_b32 m0, s31
	v_readfirstlane_b32 s31, v213
	s_add_u32 s80, s8, 0xb0000
	ds_read_b128 v[164:167], v226 offset:16384
	ds_read_b128 v[168:171], v226 offset:17408
	ds_read_b128 v[172:175], v226 offset:18432
	ds_read_b128 v[176:179], v226 offset:19456
	ds_read_b128 v[180:183], v226 offset:20480
	ds_read_b128 v[228:231], v226 offset:21504
	ds_read_b128 v[232:235], v226 offset:22528
	ds_read_b128 v[236:239], v226 offset:23552
	global_load_lds_dwordx4 v[204:205], off
	v_lshl_add_u64 v[240:241], s[8:9], 0, v[198:199]
	s_mov_b32 m0, s31
	s_addc_u32 s81, s9, 0
	v_readfirstlane_b32 s31, v214
	global_load_lds_dwordx4 v[240:241], off
	v_lshl_add_u64 v[242:243], s[80:81], 0, v[196:197]
	s_mov_b32 m0, s31
	v_readfirstlane_b32 s31, v215
	global_load_lds_dwordx4 v[242:243], off
	v_lshl_add_u64 v[242:243], s[80:81], 0, v[198:199]
	s_mov_b32 m0, s31
	v_readfirstlane_b32 s31, v211
	global_load_lds_dwordx4 v[242:243], off
	v_lshl_add_u64 v[242:243], s[52:53], 0, v[184:185]
	s_mov_b32 m0, s31
	v_readfirstlane_b32 s31, v216
	global_load_lds_dwordx4 v[242:243], off
	v_lshl_add_u64 v[244:245], s[52:53], 0, v[186:187]
	s_mov_b32 m0, s31
	s_nop 0
	global_load_lds_dwordx4 v[244:245], off
	s_waitcnt vmcnt(8)
	s_waitcnt lgkmcnt(0)
	s_barrier
	v_mfma_f32_16x16x32_bf16 v[60:63], v[132:135], v[164:167], 0
	v_mfma_f32_16x16x32_bf16 v[56:59], v[140:143], v[164:167], 0
	v_mfma_f32_16x16x32_bf16 v[44:47], v[132:135], v[172:175], 0
	v_mfma_f32_16x16x32_bf16 v[40:43], v[140:143], v[172:175], 0
	v_mfma_f32_16x16x32_bf16 v[28:31], v[132:135], v[180:183], 0
	v_mfma_f32_16x16x32_bf16 v[24:27], v[140:143], v[180:183], 0
	v_mfma_f32_16x16x32_bf16 v[12:15], v[132:135], v[232:235], 0
	v_mfma_f32_16x16x32_bf16 v[8:11], v[140:143], v[232:235], 0
	v_mfma_f32_16x16x32_bf16 v[60:63], v[136:139], v[168:171], v[60:63]
	v_mfma_f32_16x16x32_bf16 v[56:59], v[144:147], v[168:171], v[56:59]
	v_mfma_f32_16x16x32_bf16 v[44:47], v[136:139], v[176:179], v[44:47]
	v_mfma_f32_16x16x32_bf16 v[40:43], v[144:147], v[176:179], v[40:43]
	v_mfma_f32_16x16x32_bf16 v[28:31], v[136:139], v[228:231], v[28:31]
	v_mfma_f32_16x16x32_bf16 v[24:27], v[144:147], v[228:231], v[24:27]
	v_mfma_f32_16x16x32_bf16 v[12:15], v[136:139], v[236:239], v[12:15]
	v_mfma_f32_16x16x32_bf16 v[8:11], v[144:147], v[236:239], v[8:11]
	v_mfma_f32_16x16x32_bf16 v[52:55], v[148:151], v[164:167], 0
	v_mfma_f32_16x16x32_bf16 v[48:51], v[156:159], v[164:167], 0
	v_mfma_f32_16x16x32_bf16 v[36:39], v[148:151], v[172:175], 0
	v_mfma_f32_16x16x32_bf16 v[32:35], v[156:159], v[172:175], 0
	v_mfma_f32_16x16x32_bf16 v[20:23], v[148:151], v[180:183], 0
	v_mfma_f32_16x16x32_bf16 v[16:19], v[156:159], v[180:183], 0
	v_mfma_f32_16x16x32_bf16 v[4:7], v[148:151], v[232:235], 0
	v_mfma_f32_16x16x32_bf16 v[0:3], v[156:159], v[232:235], 0
	v_mfma_f32_16x16x32_bf16 v[52:55], v[152:155], v[168:171], v[52:55]
	v_mfma_f32_16x16x32_bf16 v[48:51], v[160:163], v[168:171], v[48:51]
	v_mfma_f32_16x16x32_bf16 v[36:39], v[152:155], v[176:179], v[36:39]
	v_mfma_f32_16x16x32_bf16 v[32:35], v[160:163], v[176:179], v[32:35]
	v_mfma_f32_16x16x32_bf16 v[20:23], v[152:155], v[228:231], v[20:23]
	v_mfma_f32_16x16x32_bf16 v[16:19], v[160:163], v[228:231], v[16:19]
	v_mfma_f32_16x16x32_bf16 v[4:7], v[152:155], v[236:239], v[4:7]
	v_mfma_f32_16x16x32_bf16 v[0:3], v[160:163], v[236:239], v[0:3]
	s_barrier
	s_branch .Lkmid_1441
; #define WAIT_V(n) asm volatile("s_waitcnt vmcnt(" #n ")" ::: "memory")
; #define WAIT_L(n) asm volatile("s_waitcnt lgkmcnt(" #n ")" ::: "memory")
; #define BAR __builtin_amdgcn_s_barrier()
; #define SCHED __builtin_amdgcn_sched_barrier(0)
; #define STG_A(b, h, ptr) do { const char* _g = (ptr) + (h) * ahalf; LAS unsigned char* _l = lw + ((b) * 2 + (h)) * 16384; GLDS(_g + voa0, _l); GLDS(_g + voa1, _l + 8192); } while (0)
; #define STG_B(b, h, ptr) do { const char* _g = (ptr) + (h) * bhalf; LAS unsigned char* _l = lw + 65536 + ((b) * 2 + (h)) * 16384; GLDS(_g + vob0, _l); GLDS(_g + vob1, _l + 8192); } while (0)
; #define LDA(dst, b, h) _Pragma("unroll") for (int m = 0; m < 4; ++m) _Pragma("unroll") for (int k = 0; k < 2; ++k) dst[m][k] = *(const LAS bf16x8*)(la + ((b) * 2 + (h)) * 16384 + m * 2048 + k * 1024)
; #define LDB(dst, b, h) _Pragma("unroll") for (int n = 0; n < 2; ++n) _Pragma("unroll") for (int k = 0; k < 2; ++k) dst[n][k] = *(const LAS bf16x8*)(lb + ((b) * 2 + (h)) * 16384 + n * 2048 + k * 1024)
; #define MMA(ai, bj, Af, Bf) do { __builtin_amdgcn_s_setprio(1); \
;     _Pragma("unroll") for (int m = 0; m < 4; ++m) _Pragma("unroll") for (int n = 0; n < 2; ++n) _Pragma("unroll") for (int k = 0; k < 2; ++k) \
;         acc[ai][bj][m][n] = __builtin_amdgcn_mfma_f32_16x16x32_bf16(Bf[n][k], Af[m][k], acc[ai][bj][m][n], 0, 0, 0); \
;     __builtin_amdgcn_s_setprio(0); } while (0)
; template <int BMODE, class Epi, class TileFn>
; DEV void gemm_loop(LAS unsigned char* lds, const bf16_t* __restrict__ A, int lda, const bf16_t* __restrict__ B, int ldb, int K, const Epi& epi, int t0, int tstep, int tend, const TileFn& tf) {
;     ...
;         for (int t = 0; t < nt; t += 2) {
;             const bool last = (t == nt - 2);
;             const char* a1 = cA + (size_t)(t + 1) * 128;
;             const char* a2 = last ? nA : cA + (size_t)(t + 2) * 128;
;             const char* b2 = last ? nB : cB + (size_t)(t + 2) * bks;
;             const char* a3 = a2 + 128; const char* b3 = b2 + bks;
;             LDB(B0, 0, 0); LDB(B1, 0, 1); SCHED; LDA(At, 0, 0); STG_A(1, 1, a1);
;             WAIT_V(8); WAIT_L(0); BAR; MMA(0, 0, At, B0); MMA(0, 1, At, B1); BAR; SCHED;
;             LDA(At, 0, 1); STG_B(0, 0, b2); STG_B(0, 1, b2); STG_A(0, 0, a2);
;             WAIT_V(8); WAIT_L(0); BAR; MMA(1, 0, At, B0); MMA(1, 1, At, B1); BAR; SCHED;
.LBB0_1441:
	ds_read_b128 v[132:135], v225
	ds_read_b128 v[136:139], v225 offset:1024
	ds_read_b128 v[140:143], v225 offset:2048
	ds_read_b128 v[144:147], v225 offset:3072
	ds_read_b128 v[148:151], v225 offset:16384
	ds_read_b128 v[152:155], v225 offset:17408
	ds_read_b128 v[156:159], v225 offset:18432
	ds_read_b128 v[160:163], v225 offset:19456
	s_add_u32 s8, s55, s0
	s_addc_u32 s9, s74, s1
	s_add_u32 s8, s8, 0xc366100
	s_addc_u32 s9, s9, 0
	s_add_u32 s31, s75, s0
	s_addc_u32 s80, s76, s1
	s_cmpk_eq_i32 s0, 0x1500
	s_cselect_b32 s53, s37, s9
	s_cselect_b32 s52, s30, s8
	s_cselect_b32 s9, s54, s80
	s_cselect_b32 s8, s50, s31
	v_add_u32_e32 v194, 0xc000, v211
	v_lshl_add_u64 v[204:205], v[120:121], 0, s[0:1]
	v_readfirstlane_b32 s31, v194
	v_add_u32_e32 v194, 0xe000, v211
	s_mov_b32 m0, s31
	v_readfirstlane_b32 s31, v194
	ds_read_b128 v[164:167], v226
	ds_read_b128 v[168:171], v226 offset:1024
	ds_read_b128 v[172:175], v226 offset:2048
	ds_read_b128 v[176:179], v226 offset:3072
	ds_read_b128 v[180:183], v226 offset:4096
	ds_read_b128 v[228:231], v226 offset:5120
	ds_read_b128 v[232:235], v226 offset:6144
	ds_read_b128 v[236:239], v226 offset:7168
	global_load_lds_dwordx4 v[204:205], off
	v_lshl_add_u64 v[204:205], v[122:123], 0, s[0:1]
	s_mov_b32 m0, s31
	s_nop 0
	global_load_lds_dwordx4 v[204:205], off
	s_waitcnt vmcnt(8)
	s_waitcnt lgkmcnt(0)
	s_barrier
	v_mfma_f32_16x16x32_bf16 v[128:131], v[132:135], v[164:167], v[128:131]
	v_mfma_f32_16x16x32_bf16 v[124:127], v[140:143], v[164:167], v[124:127]
	v_mfma_f32_16x16x32_bf16 v[108:111], v[132:135], v[172:175], v[108:111]
	v_mfma_f32_16x16x32_bf16 v[104:107], v[140:143], v[172:175], v[104:107]
	v_mfma_f32_16x16x32_bf16 v[92:95], v[132:135], v[180:183], v[92:95]
	v_mfma_f32_16x16x32_bf16 v[88:91], v[140:143], v[180:183], v[88:91]
	v_mfma_f32_16x16x32_bf16 v[76:79], v[132:135], v[232:235], v[76:79]
	v_mfma_f32_16x16x32_bf16 v[72:75], v[140:143], v[232:235], v[72:75]
	v_mfma_f32_16x16x32_bf16 v[128:131], v[136:139], v[168:171], v[128:131]
	v_mfma_f32_16x16x32_bf16 v[124:127], v[144:147], v[168:171], v[124:127]
	v_mfma_f32_16x16x32_bf16 v[108:111], v[136:139], v[176:179], v[108:111]
	v_mfma_f32_16x16x32_bf16 v[104:107], v[144:147], v[176:179], v[104:107]
	v_mfma_f32_16x16x32_bf16 v[92:95], v[136:139], v[228:231], v[92:95]
	v_mfma_f32_16x16x32_bf16 v[88:91], v[144:147], v[228:231], v[88:91]
	v_mfma_f32_16x16x32_bf16 v[76:79], v[136:139], v[236:239], v[76:79]
	v_mfma_f32_16x16x32_bf16 v[72:75], v[144:147], v[236:239], v[72:75]
	v_mfma_f32_16x16x32_bf16 v[116:119], v[148:151], v[164:167], v[116:119]
	v_mfma_f32_16x16x32_bf16 v[112:115], v[156:159], v[164:167], v[112:115]
	v_mfma_f32_16x16x32_bf16 v[100:103], v[148:151], v[172:175], v[100:103]
	v_mfma_f32_16x16x32_bf16 v[96:99], v[156:159], v[172:175], v[96:99]
	v_mfma_f32_16x16x32_bf16 v[84:87], v[148:151], v[180:183], v[84:87]
	v_mfma_f32_16x16x32_bf16 v[80:83], v[156:159], v[180:183], v[80:83]
	v_mfma_f32_16x16x32_bf16 v[68:71], v[148:151], v[232:235], v[68:71]
	v_mfma_f32_16x16x32_bf16 v[64:67], v[156:159], v[232:235], v[64:67]
	v_mfma_f32_16x16x32_bf16 v[116:119], v[152:155], v[168:171], v[116:119]
	v_mfma_f32_16x16x32_bf16 v[112:115], v[160:163], v[168:171], v[112:115]
	v_mfma_f32_16x16x32_bf16 v[100:103], v[152:155], v[176:179], v[100:103]
	v_mfma_f32_16x16x32_bf16 v[96:99], v[160:163], v[176:179], v[96:99]
	v_mfma_f32_16x16x32_bf16 v[84:87], v[152:155], v[228:231], v[84:87]
	v_mfma_f32_16x16x32_bf16 v[80:83], v[160:163], v[228:231], v[80:83]
	v_mfma_f32_16x16x32_bf16 v[68:71], v[152:155], v[236:239], v[68:71]
	v_mfma_f32_16x16x32_bf16 v[64:67], v[160:163], v[236:239], v[64:67]
	s_barrier
	v_readfirstlane_b32 s31, v212
	v_lshl_add_u64 v[204:205], s[8:9], 0, v[196:197]
	s_mov_b32 m0, s31
	v_readfirstlane_b32 s31, v213
	s_add_u32 s80, s8, 0xb0000
	ds_read_b128 v[164:167], v226 offset:16384
	ds_read_b128 v[168:171], v226 offset:17408
	ds_read_b128 v[172:175], v226 offset:18432
	ds_read_b128 v[176:179], v226 offset:19456
	ds_read_b128 v[180:183], v226 offset:20480
	ds_read_b128 v[228:231], v226 offset:21504
	ds_read_b128 v[232:235], v226 offset:22528
	ds_read_b128 v[236:239], v226 offset:23552
	global_load_lds_dwordx4 v[204:205], off
	v_lshl_add_u64 v[240:241], s[8:9], 0, v[198:199]
	s_mov_b32 m0, s31
	s_addc_u32 s81, s9, 0
	v_readfirstlane_b32 s31, v214
	global_load_lds_dwordx4 v[240:241], off
	v_lshl_add_u64 v[242:243], s[80:81], 0, v[196:197]
	s_mov_b32 m0, s31
	v_readfirstlane_b32 s31, v215
	global_load_lds_dwordx4 v[242:243], off
	v_lshl_add_u64 v[242:243], s[80:81], 0, v[198:199]
	s_mov_b32 m0, s31
	v_readfirstlane_b32 s31, v211
	global_load_lds_dwordx4 v[242:243], off
	v_lshl_add_u64 v[242:243], s[52:53], 0, v[184:185]
	s_mov_b32 m0, s31
	v_readfirstlane_b32 s31, v216
	global_load_lds_dwordx4 v[242:243], off
	v_lshl_add_u64 v[244:245], s[52:53], 0, v[186:187]
	s_mov_b32 m0, s31
	s_nop 0
	global_load_lds_dwordx4 v[244:245], off
	s_waitcnt vmcnt(8)
	s_waitcnt lgkmcnt(0)
	s_barrier
; #define WAIT_V(n) asm volatile("s_waitcnt vmcnt(" #n ")" ::: "memory")
; #define WAIT_L(n) asm volatile("s_waitcnt lgkmcnt(" #n ")" ::: "memory")
; #define BAR __builtin_amdgcn_s_barrier()
; #define SCHED __builtin_amdgcn_sched_barrier(0)
; #define STG_A(b, h, ptr) do { const char* _g = (ptr) + (h) * ahalf; LAS unsigned char* _l = lw + ((b) * 2 + (h)) * 16384; GLDS(_g + voa0, _l); GLDS(_g + voa1, _l + 8192); } while (0)
; #define LDA(dst, b, h) _Pragma("unroll") for (int m = 0; m < 4; ++m) _Pragma("unroll") for (int k = 0; k < 2; ++k) dst[m][k] = *(const LAS bf16x8*)(la + ((b) * 2 + (h)) * 16384 + m * 2048 + k * 1024)
; #define LDB(dst, b, h) _Pragma("unroll") for (int n = 0; n < 2; ++n) _Pragma("unroll") for (int k = 0; k < 2; ++k) dst[n][k] = *(const LAS bf16x8*)(lb + ((b) * 2 + (h)) * 16384 + n * 2048 + k * 1024)
; #define MMA(ai, bj, Af, Bf) do { __builtin_amdgcn_s_setprio(1); \
;     _Pragma("unroll") for (int m = 0; m < 4; ++m) _Pragma("unroll") for (int n = 0; n < 2; ++n) _Pragma("unroll") for (int k = 0; k < 2; ++k) \
;         acc[ai][bj][m][n] = __builtin_amdgcn_mfma_f32_16x16x32_bf16(Bf[n][k], Af[m][k], acc[ai][bj][m][n], 0, 0, 0); \
;     __builtin_amdgcn_s_setprio(0); } while (0)
; template <int BMODE, class Epi, class TileFn>
; DEV void gemm_loop(LAS unsigned char* lds, const bf16_t* __restrict__ A, int lda, const bf16_t* __restrict__ B, int ldb, int K, const Epi& epi, int t0, int tstep, int tend, const TileFn& tf) {
;     ...
;             WAIT_V(8); WAIT_L(0); BAR; MMA(1, 0, At, B0); MMA(1, 1, At, B1); BAR; SCHED;
;             LDB(B0, 1, 0); LDB(B1, 1, 1); SCHED; LDA(At, 1, 0); STG_A(0, 1, a2);
;             WAIT_V(8); WAIT_L(0); BAR; MMA(0, 0, At, B0); MMA(0, 1, At, B1); BAR; SCHED;
	v_mfma_f32_16x16x32_bf16 v[60:63], v[132:135], v[164:167], v[60:63]
	v_mfma_f32_16x16x32_bf16 v[56:59], v[140:143], v[164:167], v[56:59]
	v_mfma_f32_16x16x32_bf16 v[44:47], v[132:135], v[172:175], v[44:47]
	v_mfma_f32_16x16x32_bf16 v[40:43], v[140:143], v[172:175], v[40:43]
	v_mfma_f32_16x16x32_bf16 v[28:31], v[132:135], v[180:183], v[28:31]
	v_mfma_f32_16x16x32_bf16 v[24:27], v[140:143], v[180:183], v[24:27]
	v_mfma_f32_16x16x32_bf16 v[12:15], v[132:135], v[232:235], v[12:15]
	v_mfma_f32_16x16x32_bf16 v[8:11], v[140:143], v[232:235], v[8:11]
	v_mfma_f32_16x16x32_bf16 v[60:63], v[136:139], v[168:171], v[60:63]
	v_mfma_f32_16x16x32_bf16 v[56:59], v[144:147], v[168:171], v[56:59]
	v_mfma_f32_16x16x32_bf16 v[44:47], v[136:139], v[176:179], v[44:47]
	v_mfma_f32_16x16x32_bf16 v[40:43], v[144:147], v[176:179], v[40:43]
	v_mfma_f32_16x16x32_bf16 v[28:31], v[136:139], v[228:231], v[28:31]
	v_mfma_f32_16x16x32_bf16 v[24:27], v[144:147], v[228:231], v[24:27]
	v_mfma_f32_16x16x32_bf16 v[12:15], v[136:139], v[236:239], v[12:15]
	v_mfma_f32_16x16x32_bf16 v[8:11], v[144:147], v[236:239], v[8:11]
	v_mfma_f32_16x16x32_bf16 v[52:55], v[148:151], v[164:167], v[52:55]
	v_mfma_f32_16x16x32_bf16 v[48:51], v[156:159], v[164:167], v[48:51]
	v_mfma_f32_16x16x32_bf16 v[36:39], v[148:151], v[172:175], v[36:39]
	v_mfma_f32_16x16x32_bf16 v[32:35], v[156:159], v[172:175], v[32:35]
	v_mfma_f32_16x16x32_bf16 v[20:23], v[148:151], v[180:183], v[20:23]
	v_mfma_f32_16x16x32_bf16 v[16:19], v[156:159], v[180:183], v[16:19]
	v_mfma_f32_16x16x32_bf16 v[4:7], v[148:151], v[232:235], v[4:7]
	v_mfma_f32_16x16x32_bf16 v[0:3], v[156:159], v[232:235], v[0:3]
	v_mfma_f32_16x16x32_bf16 v[52:55], v[152:155], v[168:171], v[52:55]
	v_mfma_f32_16x16x32_bf16 v[48:51], v[160:163], v[168:171], v[48:51]
	v_mfma_f32_16x16x32_bf16 v[36:39], v[152:155], v[176:179], v[36:39]
	v_mfma_f32_16x16x32_bf16 v[32:35], v[160:163], v[176:179], v[32:35]
	v_mfma_f32_16x16x32_bf16 v[20:23], v[152:155], v[228:231], v[20:23]
	v_mfma_f32_16x16x32_bf16 v[16:19], v[160:163], v[228:231], v[16:19]
	v_mfma_f32_16x16x32_bf16 v[4:7], v[152:155], v[236:239], v[4:7]
	v_mfma_f32_16x16x32_bf16 v[0:3], v[160:163], v[236:239], v[0:3]
	s_barrier
.Lkmid_1441:
	ds_read_b128 v[132:135], v225 offset:32768
	ds_read_b128 v[136:139], v225 offset:33792
	ds_read_b128 v[140:143], v225 offset:34816
	ds_read_b128 v[144:147], v225 offset:35840
	ds_read_b128 v[148:151], v225 offset:49152
	ds_read_b128 v[152:155], v225 offset:50176
	ds_read_b128 v[156:159], v225 offset:51200
	ds_read_b128 v[160:163], v225 offset:52224
	s_add_u32 s52, s52, 0xb0000
	s_addc_u32 s53, s53, 0
	v_readfirstlane_b32 s31, v217
	v_lshl_add_u64 v[246:247], s[52:53], 0, v[184:185]
	s_mov_b32 m0, s31
	v_readfirstlane_b32 s31, v218
	ds_read_b128 v[164:167], v226 offset:32768
	ds_read_b128 v[168:171], v226 offset:33792
	ds_read_b128 v[172:175], v226 offset:34816
	ds_read_b128 v[176:179], v226 offset:35840
	ds_read_b128 v[180:183], v226 offset:36864
	ds_read_b128 v[228:231], v226 offset:37888
	ds_read_b128 v[232:235], v226 offset:38912
	ds_read_b128 v[236:239], v226 offset:39936
	global_load_lds_dwordx4 v[246:247], off
	v_lshl_add_u64 v[246:247], s[52:53], 0, v[186:187]
	s_mov_b32 m0, s31
	s_nop 0
	global_load_lds_dwordx4 v[246:247], off
	s_waitcnt vmcnt(8)
	s_waitcnt lgkmcnt(0)
	s_barrier
	v_mfma_f32_16x16x32_bf16 v[128:131], v[132:135], v[164:167], v[128:131]
	v_mfma_f32_16x16x32_bf16 v[124:127], v[140:143], v[164:167], v[124:127]
	v_mfma_f32_16x16x32_bf16 v[108:111], v[132:135], v[172:175], v[108:111]
	v_mfma_f32_16x16x32_bf16 v[104:107], v[140:143], v[172:175], v[104:107]
	v_mfma_f32_16x16x32_bf16 v[92:95], v[132:135], v[180:183], v[92:95]
	v_mfma_f32_16x16x32_bf16 v[88:91], v[140:143], v[180:183], v[88:91]
	v_mfma_f32_16x16x32_bf16 v[76:79], v[132:135], v[232:235], v[76:79]
	v_mfma_f32_16x16x32_bf16 v[72:75], v[140:143], v[232:235], v[72:75]
	v_mfma_f32_16x16x32_bf16 v[128:131], v[136:139], v[168:171], v[128:131]
	v_mfma_f32_16x16x32_bf16 v[124:127], v[144:147], v[168:171], v[124:127]
	v_mfma_f32_16x16x32_bf16 v[108:111], v[136:139], v[176:179], v[108:111]
	v_mfma_f32_16x16x32_bf16 v[104:107], v[144:147], v[176:179], v[104:107]
	v_mfma_f32_16x16x32_bf16 v[92:95], v[136:139], v[228:231], v[92:95]
	v_mfma_f32_16x16x32_bf16 v[88:91], v[144:147], v[228:231], v[88:91]
	v_mfma_f32_16x16x32_bf16 v[76:79], v[136:139], v[236:239], v[76:79]
	v_mfma_f32_16x16x32_bf16 v[72:75], v[144:147], v[236:239], v[72:75]
	v_mfma_f32_16x16x32_bf16 v[116:119], v[148:151], v[164:167], v[116:119]
	v_mfma_f32_16x16x32_bf16 v[112:115], v[156:159], v[164:167], v[112:115]
	v_mfma_f32_16x16x32_bf16 v[100:103], v[148:151], v[172:175], v[100:103]
	v_mfma_f32_16x16x32_bf16 v[96:99], v[156:159], v[172:175], v[96:99]
	v_mfma_f32_16x16x32_bf16 v[84:87], v[148:151], v[180:183], v[84:87]
	v_mfma_f32_16x16x32_bf16 v[80:83], v[156:159], v[180:183], v[80:83]
	v_mfma_f32_16x16x32_bf16 v[68:71], v[148:151], v[232:235], v[68:71]
	v_mfma_f32_16x16x32_bf16 v[64:67], v[156:159], v[232:235], v[64:67]
	v_mfma_f32_16x16x32_bf16 v[116:119], v[152:155], v[168:171], v[116:119]
	v_mfma_f32_16x16x32_bf16 v[112:115], v[160:163], v[168:171], v[112:115]
	v_mfma_f32_16x16x32_bf16 v[100:103], v[152:155], v[176:179], v[100:103]
	v_mfma_f32_16x16x32_bf16 v[96:99], v[160:163], v[176:179], v[96:99]
	v_mfma_f32_16x16x32_bf16 v[84:87], v[152:155], v[228:231], v[84:87]
	v_mfma_f32_16x16x32_bf16 v[80:83], v[160:163], v[228:231], v[80:83]
	v_mfma_f32_16x16x32_bf16 v[68:71], v[152:155], v[236:239], v[68:71]
	v_mfma_f32_16x16x32_bf16 v[64:67], v[160:163], v[236:239], v[64:67]
	s_barrier
; #define WAIT_V(n) asm volatile("s_waitcnt vmcnt(" #n ")" ::: "memory")
; #define WAIT_L(n) asm volatile("s_waitcnt lgkmcnt(" #n ")" ::: "memory")
; #define BAR __builtin_amdgcn_s_barrier()
; #define SCHED __builtin_amdgcn_sched_barrier(0)
; #define STG_A(b, h, ptr) do { const char* _g = (ptr) + (h) * ahalf; LAS unsigned char* _l = lw + ((b) * 2 + (h)) * 16384; GLDS(_g + voa0, _l); GLDS(_g + voa1, _l + 8192); } while (0)
; #define STG_B(b, h, ptr) do { const char* _g = (ptr) + (h) * bhalf; LAS unsigned char* _l = lw + 65536 + ((b) * 2 + (h)) * 16384; GLDS(_g + vob0, _l); GLDS(_g + vob1, _l + 8192); } while (0)
; #define LDA(dst, b, h) _Pragma("unroll") for (int m = 0; m < 4; ++m) _Pragma("unroll") for (int k = 0; k < 2; ++k) dst[m][k] = *(const LAS bf16x8*)(la + ((b) * 2 + (h)) * 16384 + m * 2048 + k * 1024)
; #define MMA(ai, bj, Af, Bf) do { __builtin_amdgcn_s_setprio(1); \
;     _Pragma("unroll") for (int m = 0; m < 4; ++m) _Pragma("unroll") for (int n = 0; n < 2; ++n) _Pragma("unroll") for (int k = 0; k < 2; ++k) \
;         acc[ai][bj][m][n] = __builtin_amdgcn_mfma_f32_16x16x32_bf16(Bf[n][k], Af[m][k], acc[ai][bj][m][n], 0, 0, 0); \
;     __builtin_amdgcn_s_setprio(0); } while (0)
; template <int BMODE, class Epi, class TileFn>
; DEV void gemm_loop(LAS unsigned char* lds, const bf16_t* __restrict__ A, int lda, const bf16_t* __restrict__ B, int ldb, int K, const Epi& epi, int t0, int tstep, int tend, const TileFn& tf) {
;     ...
;             LDA(At, 1, 1); STG_B(1, 0, b3); STG_B(1, 1, b3); STG_A(1, 0, a3);
;             WAIT_V(8); WAIT_L(0); BAR; MMA(1, 0, At, B0); MMA(1, 1, At, B1); BAR; SCHED;
;         }
;         if (wr == 0) BAR;
	v_readfirstlane_b32 s31, v219
	v_lshl_add_u64 v[204:205], v[204:205], 0, s[2:3]
	s_mov_b32 m0, s31
	v_readfirstlane_b32 s31, v220
	s_add_u32 s8, s8, 0xb0080
	ds_read_b128 v[164:167], v226 offset:49152
	ds_read_b128 v[168:171], v226 offset:50176
	ds_read_b128 v[172:175], v226 offset:51200
	ds_read_b128 v[176:179], v226 offset:52224
	ds_read_b128 v[180:183], v226 offset:53248
	ds_read_b128 v[228:231], v226 offset:54272
	ds_read_b128 v[232:235], v226 offset:55296
	ds_read_b128 v[236:239], v226 offset:56320
	global_load_lds_dwordx4 v[204:205], off
	v_lshl_add_u64 v[204:205], v[240:241], 0, s[2:3]
	s_mov_b32 m0, s31
	s_addc_u32 s9, s9, 0
	v_readfirstlane_b32 s31, v223
	global_load_lds_dwordx4 v[204:205], off
	v_lshl_add_u64 v[204:205], s[8:9], 0, v[196:197]
	s_mov_b32 m0, s31
	s_nop 0
	global_load_lds_dwordx4 v[204:205], off
	v_lshl_add_u64 v[204:205], s[8:9], 0, v[198:199]
	v_readfirstlane_b32 s8, v224
	s_mov_b32 m0, s8
	v_readfirstlane_b32 s8, v221
	global_load_lds_dwordx4 v[204:205], off
	v_lshl_add_u64 v[204:205], v[242:243], 0, s[2:3]
	s_mov_b32 m0, s8
	v_readfirstlane_b32 s8, v222
	global_load_lds_dwordx4 v[204:205], off
	v_lshl_add_u64 v[204:205], v[244:245], 0, s[2:3]
	s_mov_b32 m0, s8
	s_nop 0
	global_load_lds_dwordx4 v[204:205], off
	s_waitcnt vmcnt(8)
	s_waitcnt lgkmcnt(0)
	s_barrier
	v_mfma_f32_16x16x32_bf16 v[60:63], v[132:135], v[164:167], v[60:63]
	v_mfma_f32_16x16x32_bf16 v[56:59], v[140:143], v[164:167], v[56:59]
	v_mfma_f32_16x16x32_bf16 v[44:47], v[132:135], v[172:175], v[44:47]
	v_mfma_f32_16x16x32_bf16 v[40:43], v[140:143], v[172:175], v[40:43]
	v_mfma_f32_16x16x32_bf16 v[28:31], v[132:135], v[180:183], v[28:31]
	v_mfma_f32_16x16x32_bf16 v[24:27], v[140:143], v[180:183], v[24:27]
	v_mfma_f32_16x16x32_bf16 v[12:15], v[132:135], v[232:235], v[12:15]
	v_mfma_f32_16x16x32_bf16 v[8:11], v[140:143], v[232:235], v[8:11]
	v_mfma_f32_16x16x32_bf16 v[60:63], v[136:139], v[168:171], v[60:63]
	v_mfma_f32_16x16x32_bf16 v[56:59], v[144:147], v[168:171], v[56:59]
	v_mfma_f32_16x16x32_bf16 v[44:47], v[136:139], v[176:179], v[44:47]
	v_mfma_f32_16x16x32_bf16 v[40:43], v[144:147], v[176:179], v[40:43]
	v_mfma_f32_16x16x32_bf16 v[28:31], v[136:139], v[228:231], v[28:31]
	v_mfma_f32_16x16x32_bf16 v[24:27], v[144:147], v[228:231], v[24:27]
	v_mfma_f32_16x16x32_bf16 v[12:15], v[136:139], v[236:239], v[12:15]
	v_mfma_f32_16x16x32_bf16 v[8:11], v[144:147], v[236:239], v[8:11]
	v_mfma_f32_16x16x32_bf16 v[52:55], v[148:151], v[164:167], v[52:55]
	v_mfma_f32_16x16x32_bf16 v[48:51], v[156:159], v[164:167], v[48:51]
	v_mfma_f32_16x16x32_bf16 v[36:39], v[148:151], v[172:175], v[36:39]
	v_mfma_f32_16x16x32_bf16 v[32:35], v[156:159], v[172:175], v[32:35]
	v_mfma_f32_16x16x32_bf16 v[20:23], v[148:151], v[180:183], v[20:23]
	v_mfma_f32_16x16x32_bf16 v[16:19], v[156:159], v[180:183], v[16:19]
	v_mfma_f32_16x16x32_bf16 v[4:7], v[148:151], v[232:235], v[4:7]
	v_mfma_f32_16x16x32_bf16 v[0:3], v[156:159], v[232:235], v[0:3]
	v_mfma_f32_16x16x32_bf16 v[52:55], v[152:155], v[168:171], v[52:55]
	v_mfma_f32_16x16x32_bf16 v[48:51], v[160:163], v[168:171], v[48:51]
	v_mfma_f32_16x16x32_bf16 v[36:39], v[152:155], v[176:179], v[36:39]
	v_mfma_f32_16x16x32_bf16 v[32:35], v[160:163], v[176:179], v[32:35]
	v_mfma_f32_16x16x32_bf16 v[20:23], v[152:155], v[228:231], v[20:23]
	v_mfma_f32_16x16x32_bf16 v[16:19], v[160:163], v[228:231], v[16:19]
	v_mfma_f32_16x16x32_bf16 v[4:7], v[152:155], v[236:239], v[4:7]
	v_mfma_f32_16x16x32_bf16 v[0:3], v[160:163], v[236:239], v[0:3]
	s_barrier
	s_add_i32 s77, s77, 2
	s_add_u32 s0, s0, 0x100
	s_addc_u32 s1, s1, 0
	s_cmp_gt_u32 s77, 41
	s_cbranch_scc0 .LBB0_1441
	s_setprio 0
	s_and_saveexec_b64 s[0:1], s[40:41]
	s_cbranch_execz .LBB0_1444
	s_barrier
